# GEMM K-loops: redundant post-barrier lgkmcnt wait dropped, setprio 1 issued before the barrier, mid-segment setprio pair removed
# speedup vs baseline: 1.0046x; 1.0038x over previous
; #define PG8_STAGE(bufoff, gbase, voff) do { _Pragma("unroll") for (int _i = 0; _i < 2; ++_i) \
;         __builtin_amdgcn_global_load_lds((const unsigned*)((const char*)(gbase) + (voff)[_i]), (LAS unsigned*)(lds + (bufoff) + ldsw + _i * 8192), 16, 0, 0); } while (0)
; #define PG8_LDA(dst, b, h) do { _Pragma("unroll") for (int m = 0; m < 4; ++m) _Pragma("unroll") for (int k = 0; k < 2; ++k) dst[m][k] = *(const LAS bf16x8*)(lds + PG8_SA(b, h) + aoff + m * 2048 + k * 1024); } while (0)
; #define PG8_LDB(dst, b, h) do { _Pragma("unroll") for (int n = 0; n < 2; ++n) _Pragma("unroll") for (int k = 0; k < 2; ++k) dst[n][k] = *(const LAS bf16x8*)(lds + PG8_SB(b, h) + boff + n * 2048 + k * 1024); } while (0)
; #define PG8_MMA(ai, bj, At, Bt) do { __builtin_amdgcn_s_setprio(1); _Pragma("unroll") for (int m = 0; m < 4; ++m) _Pragma("unroll") for (int n = 0; n < 2; ++n) _Pragma("unroll") for (int k = 0; k < 2; ++k) \
;         acc[ai][bj][m][n] = __builtin_amdgcn_mfma_f32_16x16x32_bf16(Bt[n][k], At[m][k], acc[ai][bj][m][n], 0, 0, 0); __builtin_amdgcn_s_setprio(0); } while (0)
; #define PG8_WAIT_V(n) asm volatile("s_waitcnt vmcnt(" #n ")" ::: "memory")
; template <class Epi, int AMODE>
; __device__ __forceinline__ void gemm_phase(LAS unsigned char* lds, const Gemm g, const StaticOrder& S, const Epi& E, int stagger_us, int tid_in) {
;     ...
;             PG8_LDB(B0, 0, 0); PG8_LDB(B1, 0, 1); PG8_SCHED; PG8_LDA(At, 0, 0); PG8_STAGE(PG8_SA(1, 1), a1 + hstepA, voffA);
;             PG8_WAIT_V(8); PG8_WAIT_L(0); PG8_BAR; PG8_MMA(0, 0, At, B0); PG8_MMA(0, 1, At, B1); PG8_BAR; PG8_SCHED;
;             PG8_LDA(At, 0, 1); PG8_STAGE(PG8_SB(0, 0), b2, voffB); PG8_STAGE(PG8_SB(0, 1), b2 + hstepB, voffB); PG8_STAGE(PG8_SA(0, 0), a2, voffA);
;             PG8_WAIT_V(8); PG8_WAIT_L(0); PG8_BAR; PG8_MMA(1, 0, At, B0); PG8_MMA(1, 1, At, B1); PG8_BAR; PG8_SCHED;
;             PG8_LDB(B0, 1, 0); PG8_LDB(B1, 1, 1); PG8_SCHED; PG8_LDA(At, 1, 0); PG8_STAGE(PG8_SA(0, 1), a2 + hstepA, voffA);
;             PG8_WAIT_V(8); PG8_WAIT_L(0); PG8_BAR; PG8_MMA(0, 0, At, B0); PG8_MMA(0, 1, At, B1); PG8_BAR; PG8_SCHED;
;             PG8_LDA(At, 1, 1); PG8_STAGE(PG8_SB(1, 0), b3, voffB); PG8_STAGE(PG8_SB(1, 1), b3 + hstepB, voffB); PG8_STAGE(PG8_SA(1, 0), a3, voffA);
;             PG8_WAIT_V(8); PG8_WAIT_L(0); PG8_BAR; PG8_MMA(1, 0, At, B0); PG8_MMA(1, 1, At, B1); PG8_BAR; PG8_SCHED;
.LBB0_396:
	s_add_u32 s4, s60, 0xfff80080
	s_addc_u32 s5, s61, -1
	s_add_i32 s30, 0, 0x10000
	s_cmp_eq_u32 s29, 28
	s_cselect_b32 s7, s27, s5
	s_cselect_b32 s6, s28, s4
	v_add_u32_e32 v140, s30, v162
	s_cselect_b32 s5, s49, vcc_hi
	s_cselect_b32 s4, s51, vcc_lo
	s_add_i32 s44, 0, 0x14000
	ds_read_b128 v[144:147], v140
	ds_read_b128 v[148:151], v140 offset:1024
	ds_read_b128 v[152:155], v140 offset:2048
	ds_read_b128 v[156:159], v140 offset:3072
	v_add_u32_e32 v140, s44, v162
	ds_read_b128 v[166:169], v140
	ds_read_b128 v[170:173], v140 offset:1024
	ds_read_b128 v[174:177], v140 offset:2048
	ds_read_b128 v[178:181], v140 offset:3072
	v_lshl_add_u64 v[140:141], s[60:61], 0, v[136:137]
	s_add_i32 m0, s57, 0xc000
	ds_read_b128 v[182:185], v164
	ds_read_b128 v[186:189], v164 offset:1024
	ds_read_b128 v[190:193], v164 offset:2048
	ds_read_b128 v[194:197], v164 offset:3072
	ds_read_b128 v[198:201], v164 offset:4096
	ds_read_b128 v[202:205], v164 offset:5120
	ds_read_b128 v[206:209], v164 offset:6144
	ds_read_b128 v[210:213], v164 offset:7168
	global_load_lds_dwordx4 v[140:141], off
	v_lshl_add_u64 v[140:141], s[60:61], 0, v[138:139]
	s_add_i32 m0, s57, 0xe000
	s_nop 0
	global_load_lds_dwordx4 v[140:141], off
	s_waitcnt vmcnt(8)
	s_waitcnt lgkmcnt(0)
	s_setprio 1
	s_barrier
	v_mfma_f32_16x16x32_bf16 v[126:129], v[144:147], v[182:185], v[126:129]
	v_mfma_f32_16x16x32_bf16 v[122:125], v[152:155], v[182:185], v[122:125]
	v_mfma_f32_16x16x32_bf16 v[110:113], v[144:147], v[190:193], v[110:113]
	v_mfma_f32_16x16x32_bf16 v[106:109], v[152:155], v[190:193], v[106:109]
	v_mfma_f32_16x16x32_bf16 v[94:97], v[144:147], v[198:201], v[94:97]
	v_mfma_f32_16x16x32_bf16 v[90:93], v[152:155], v[198:201], v[90:93]
	v_mfma_f32_16x16x32_bf16 v[78:81], v[144:147], v[206:209], v[78:81]
	v_mfma_f32_16x16x32_bf16 v[74:77], v[152:155], v[206:209], v[74:77]
	v_mfma_f32_16x16x32_bf16 v[126:129], v[148:151], v[186:189], v[126:129]
	v_mfma_f32_16x16x32_bf16 v[122:125], v[156:159], v[186:189], v[122:125]
	v_mfma_f32_16x16x32_bf16 v[110:113], v[148:151], v[194:197], v[110:113]
	v_mfma_f32_16x16x32_bf16 v[106:109], v[156:159], v[194:197], v[106:109]
	v_mfma_f32_16x16x32_bf16 v[94:97], v[148:151], v[202:205], v[94:97]
	v_mfma_f32_16x16x32_bf16 v[90:93], v[156:159], v[202:205], v[90:93]
	v_mfma_f32_16x16x32_bf16 v[78:81], v[148:151], v[210:213], v[78:81]
	v_mfma_f32_16x16x32_bf16 v[74:77], v[156:159], v[210:213], v[74:77]
	v_mfma_f32_16x16x32_bf16 v[118:121], v[166:169], v[182:185], v[118:121]
	v_mfma_f32_16x16x32_bf16 v[114:117], v[174:177], v[182:185], v[114:117]
	v_mfma_f32_16x16x32_bf16 v[102:105], v[166:169], v[190:193], v[102:105]
	v_mfma_f32_16x16x32_bf16 v[98:101], v[174:177], v[190:193], v[98:101]
	v_mfma_f32_16x16x32_bf16 v[86:89], v[166:169], v[198:201], v[86:89]
	v_mfma_f32_16x16x32_bf16 v[82:85], v[174:177], v[198:201], v[82:85]
	v_mfma_f32_16x16x32_bf16 v[70:73], v[166:169], v[206:209], v[70:73]
	v_mfma_f32_16x16x32_bf16 v[66:69], v[174:177], v[206:209], v[66:69]
	v_mfma_f32_16x16x32_bf16 v[118:121], v[170:173], v[186:189], v[118:121]
	v_mfma_f32_16x16x32_bf16 v[114:117], v[178:181], v[186:189], v[114:117]
	v_mfma_f32_16x16x32_bf16 v[102:105], v[170:173], v[194:197], v[102:105]
	v_mfma_f32_16x16x32_bf16 v[98:101], v[178:181], v[194:197], v[98:101]
	v_mfma_f32_16x16x32_bf16 v[86:89], v[170:173], v[202:205], v[86:89]
	v_mfma_f32_16x16x32_bf16 v[82:85], v[178:181], v[202:205], v[82:85]
	v_mfma_f32_16x16x32_bf16 v[70:73], v[170:173], v[210:213], v[70:73]
	v_mfma_f32_16x16x32_bf16 v[66:69], v[178:181], v[210:213], v[66:69]
	s_setprio 0
	s_barrier
	s_add_i32 s30, s30, s66
	v_lshl_add_u64 v[140:141], s[4:5], 0, v[0:1]
	s_mov_b32 m0, s30
	ds_read_b128 v[182:185], v164 offset:16384
	ds_read_b128 v[186:189], v164 offset:17408
	ds_read_b128 v[190:193], v164 offset:18432
	ds_read_b128 v[194:197], v164 offset:19456
	ds_read_b128 v[198:201], v164 offset:20480
	ds_read_b128 v[202:205], v164 offset:21504
	ds_read_b128 v[206:209], v164 offset:22528
	ds_read_b128 v[210:213], v164 offset:23552
	global_load_lds_dwordx4 v[140:141], off
	s_add_i32 m0, s30, 0x2000
	s_add_u32 s30, s4, 0x80000
	v_lshl_add_u64 v[160:161], s[4:5], 0, v[130:131]
	s_addc_u32 s31, s5, 0
	s_add_i32 s44, s44, s66
	global_load_lds_dwordx4 v[160:161], off
	v_lshl_add_u64 v[214:215], s[30:31], 0, v[0:1]
	s_mov_b32 m0, s44
	v_lshl_add_u64 v[216:217], s[6:7], 0, v[132:133]
	global_load_lds_dwordx4 v[214:215], off
	v_lshl_add_u64 v[214:215], s[30:31], 0, v[130:131]
	s_add_i32 m0, s44, 0x2000
	s_nop 0
	global_load_lds_dwordx4 v[214:215], off
	v_lshl_add_u64 v[214:215], s[6:7], 0, v[134:135]
	s_mov_b32 m0, s57
	s_nop 0
	global_load_lds_dwordx4 v[214:215], off
	s_mov_b32 m0, s59
	s_nop 0
	global_load_lds_dwordx4 v[216:217], off
	s_waitcnt vmcnt(8)
	s_waitcnt lgkmcnt(0)
	s_setprio 1
	s_barrier
; #define PG8_STAGE(bufoff, gbase, voff) do { _Pragma("unroll") for (int _i = 0; _i < 2; ++_i) \
;         __builtin_amdgcn_global_load_lds((const unsigned*)((const char*)(gbase) + (voff)[_i]), (LAS unsigned*)(lds + (bufoff) + ldsw + _i * 8192), 16, 0, 0); } while (0)
; #define PG8_LDA(dst, b, h) do { _Pragma("unroll") for (int m = 0; m < 4; ++m) _Pragma("unroll") for (int k = 0; k < 2; ++k) dst[m][k] = *(const LAS bf16x8*)(lds + PG8_SA(b, h) + aoff + m * 2048 + k * 1024); } while (0)
; #define PG8_LDB(dst, b, h) do { _Pragma("unroll") for (int n = 0; n < 2; ++n) _Pragma("unroll") for (int k = 0; k < 2; ++k) dst[n][k] = *(const LAS bf16x8*)(lds + PG8_SB(b, h) + boff + n * 2048 + k * 1024); } while (0)
; #define PG8_MMA(ai, bj, At, Bt) do { __builtin_amdgcn_s_setprio(1); _Pragma("unroll") for (int m = 0; m < 4; ++m) _Pragma("unroll") for (int n = 0; n < 2; ++n) _Pragma("unroll") for (int k = 0; k < 2; ++k) \
;         acc[ai][bj][m][n] = __builtin_amdgcn_mfma_f32_16x16x32_bf16(Bt[n][k], At[m][k], acc[ai][bj][m][n], 0, 0, 0); __builtin_amdgcn_s_setprio(0); } while (0)
; #define PG8_WAIT_V(n) asm volatile("s_waitcnt vmcnt(" #n ")" ::: "memory")
; template <class Epi, int AMODE>
; __device__ __forceinline__ void gemm_phase(LAS unsigned char* lds, const Gemm g, const StaticOrder& S, const Epi& E, int stagger_us, int tid_in) {
;     ...
;             PG8_LDB(B0, 0, 0); PG8_LDB(B1, 0, 1); PG8_SCHED; PG8_LDA(At, 0, 0); PG8_STAGE(PG8_SA(1, 1), a1 + hstepA, voffA);
;             PG8_WAIT_V(8); PG8_WAIT_L(0); PG8_BAR; PG8_MMA(0, 0, At, B0); PG8_MMA(0, 1, At, B1); PG8_BAR; PG8_SCHED;
;             PG8_LDA(At, 0, 1); PG8_STAGE(PG8_SB(0, 0), b2, voffB); PG8_STAGE(PG8_SB(0, 1), b2 + hstepB, voffB); PG8_STAGE(PG8_SA(0, 0), a2, voffA);
;             PG8_WAIT_V(8); PG8_WAIT_L(0); PG8_BAR; PG8_MMA(1, 0, At, B0); PG8_MMA(1, 1, At, B1); PG8_BAR; PG8_SCHED;
;             PG8_LDB(B0, 1, 0); PG8_LDB(B1, 1, 1); PG8_SCHED; PG8_LDA(At, 1, 0); PG8_STAGE(PG8_SA(0, 1), a2 + hstepA, voffA);
;             PG8_WAIT_V(8); PG8_WAIT_L(0); PG8_BAR; PG8_MMA(0, 0, At, B0); PG8_MMA(0, 1, At, B1); PG8_BAR; PG8_SCHED;
;             PG8_LDA(At, 1, 1); PG8_STAGE(PG8_SB(1, 0), b3, voffB); PG8_STAGE(PG8_SB(1, 1), b3 + hstepB, voffB); PG8_STAGE(PG8_SA(1, 0), a3, voffA);
;             PG8_WAIT_V(8); PG8_WAIT_L(0); PG8_BAR; PG8_MMA(1, 0, At, B0); PG8_MMA(1, 1, At, B1); PG8_BAR; PG8_SCHED;
	v_mfma_f32_16x16x32_bf16 v[62:65], v[144:147], v[182:185], v[62:65]
	v_mfma_f32_16x16x32_bf16 v[58:61], v[152:155], v[182:185], v[58:61]
	v_mfma_f32_16x16x32_bf16 v[46:49], v[144:147], v[190:193], v[46:49]
	v_mfma_f32_16x16x32_bf16 v[42:45], v[152:155], v[190:193], v[42:45]
	v_mfma_f32_16x16x32_bf16 v[30:33], v[144:147], v[198:201], v[30:33]
	v_mfma_f32_16x16x32_bf16 v[26:29], v[152:155], v[198:201], v[26:29]
	v_mfma_f32_16x16x32_bf16 v[14:17], v[144:147], v[206:209], v[14:17]
	v_mfma_f32_16x16x32_bf16 v[10:13], v[152:155], v[206:209], v[10:13]
	v_mfma_f32_16x16x32_bf16 v[62:65], v[148:151], v[186:189], v[62:65]
	v_mfma_f32_16x16x32_bf16 v[58:61], v[156:159], v[186:189], v[58:61]
	v_mfma_f32_16x16x32_bf16 v[46:49], v[148:151], v[194:197], v[46:49]
	v_mfma_f32_16x16x32_bf16 v[42:45], v[156:159], v[194:197], v[42:45]
	v_mfma_f32_16x16x32_bf16 v[30:33], v[148:151], v[202:205], v[30:33]
	v_mfma_f32_16x16x32_bf16 v[26:29], v[156:159], v[202:205], v[26:29]
	v_mfma_f32_16x16x32_bf16 v[14:17], v[148:151], v[210:213], v[14:17]
	v_mfma_f32_16x16x32_bf16 v[10:13], v[156:159], v[210:213], v[10:13]
	v_mfma_f32_16x16x32_bf16 v[54:57], v[166:169], v[182:185], v[54:57]
	v_mfma_f32_16x16x32_bf16 v[50:53], v[174:177], v[182:185], v[50:53]
	v_mfma_f32_16x16x32_bf16 v[38:41], v[166:169], v[190:193], v[38:41]
	v_mfma_f32_16x16x32_bf16 v[34:37], v[174:177], v[190:193], v[34:37]
	v_mfma_f32_16x16x32_bf16 v[22:25], v[166:169], v[198:201], v[22:25]
	v_mfma_f32_16x16x32_bf16 v[18:21], v[174:177], v[198:201], v[18:21]
	v_mfma_f32_16x16x32_bf16 v[6:9], v[166:169], v[206:209], v[6:9]
	v_mfma_f32_16x16x32_bf16 v[2:5], v[174:177], v[206:209], v[2:5]
	v_mfma_f32_16x16x32_bf16 v[54:57], v[170:173], v[186:189], v[54:57]
	v_mfma_f32_16x16x32_bf16 v[50:53], v[178:181], v[186:189], v[50:53]
	v_mfma_f32_16x16x32_bf16 v[38:41], v[170:173], v[194:197], v[38:41]
	v_mfma_f32_16x16x32_bf16 v[34:37], v[178:181], v[194:197], v[34:37]
	v_mfma_f32_16x16x32_bf16 v[22:25], v[170:173], v[202:205], v[22:25]
	v_mfma_f32_16x16x32_bf16 v[18:21], v[178:181], v[202:205], v[18:21]
	v_mfma_f32_16x16x32_bf16 v[6:9], v[170:173], v[210:213], v[6:9]
	v_mfma_f32_16x16x32_bf16 v[2:5], v[178:181], v[210:213], v[2:5]
	s_setprio 0
	s_barrier
	s_add_i32 s30, 0, 0x18000
	v_add_u32_e32 v142, s30, v162
	s_add_i32 s31, 0, 0x1c000
	ds_read_b128 v[144:147], v142
	ds_read_b128 v[148:151], v142 offset:1024
	ds_read_b128 v[152:155], v142 offset:2048
	ds_read_b128 v[156:159], v142 offset:3072
	v_add_u32_e32 v142, s31, v162
	ds_read_b128 v[166:169], v142
	ds_read_b128 v[170:173], v142 offset:1024
	ds_read_b128 v[174:177], v142 offset:2048
	ds_read_b128 v[178:181], v142 offset:3072
	s_add_u32 s6, s6, 0x80000
	s_addc_u32 s7, s7, 0
	s_mov_b32 m0, s87
	v_lshl_add_u64 v[218:219], s[6:7], 0, v[134:135]
	ds_read_b128 v[182:185], v164 offset:32768
	ds_read_b128 v[186:189], v164 offset:33792
	ds_read_b128 v[190:193], v164 offset:34816
	ds_read_b128 v[194:197], v164 offset:35840
	ds_read_b128 v[198:201], v164 offset:36864
	ds_read_b128 v[202:205], v164 offset:37888
	ds_read_b128 v[206:209], v164 offset:38912
	ds_read_b128 v[210:213], v164 offset:39936
	global_load_lds_dwordx4 v[218:219], off
	v_lshl_add_u64 v[218:219], s[6:7], 0, v[132:133]
	s_mov_b32 m0, s91
	s_nop 0
	global_load_lds_dwordx4 v[218:219], off
	s_waitcnt vmcnt(8)
	s_waitcnt lgkmcnt(0)
	s_setprio 1
	s_barrier
	v_mfma_f32_16x16x32_bf16 v[126:129], v[144:147], v[182:185], v[126:129]
	v_mfma_f32_16x16x32_bf16 v[122:125], v[152:155], v[182:185], v[122:125]
	v_mfma_f32_16x16x32_bf16 v[110:113], v[144:147], v[190:193], v[110:113]
	v_mfma_f32_16x16x32_bf16 v[106:109], v[152:155], v[190:193], v[106:109]
	v_mfma_f32_16x16x32_bf16 v[94:97], v[144:147], v[198:201], v[94:97]
	v_mfma_f32_16x16x32_bf16 v[90:93], v[152:155], v[198:201], v[90:93]
	v_mfma_f32_16x16x32_bf16 v[78:81], v[144:147], v[206:209], v[78:81]
	v_mfma_f32_16x16x32_bf16 v[74:77], v[152:155], v[206:209], v[74:77]
	v_mfma_f32_16x16x32_bf16 v[126:129], v[148:151], v[186:189], v[126:129]
	v_mfma_f32_16x16x32_bf16 v[122:125], v[156:159], v[186:189], v[122:125]
	v_mfma_f32_16x16x32_bf16 v[110:113], v[148:151], v[194:197], v[110:113]
	v_mfma_f32_16x16x32_bf16 v[106:109], v[156:159], v[194:197], v[106:109]
	v_mfma_f32_16x16x32_bf16 v[94:97], v[148:151], v[202:205], v[94:97]
	v_mfma_f32_16x16x32_bf16 v[90:93], v[156:159], v[202:205], v[90:93]
	v_mfma_f32_16x16x32_bf16 v[78:81], v[148:151], v[210:213], v[78:81]
	v_mfma_f32_16x16x32_bf16 v[74:77], v[156:159], v[210:213], v[74:77]
	v_mfma_f32_16x16x32_bf16 v[118:121], v[166:169], v[182:185], v[118:121]
	v_mfma_f32_16x16x32_bf16 v[114:117], v[174:177], v[182:185], v[114:117]
	v_mfma_f32_16x16x32_bf16 v[102:105], v[166:169], v[190:193], v[102:105]
	v_mfma_f32_16x16x32_bf16 v[98:101], v[174:177], v[190:193], v[98:101]
	v_mfma_f32_16x16x32_bf16 v[86:89], v[166:169], v[198:201], v[86:89]
	v_mfma_f32_16x16x32_bf16 v[82:85], v[174:177], v[198:201], v[82:85]
	v_mfma_f32_16x16x32_bf16 v[70:73], v[166:169], v[206:209], v[70:73]
	v_mfma_f32_16x16x32_bf16 v[66:69], v[174:177], v[206:209], v[66:69]
	v_mfma_f32_16x16x32_bf16 v[118:121], v[170:173], v[186:189], v[118:121]
	v_mfma_f32_16x16x32_bf16 v[114:117], v[178:181], v[186:189], v[114:117]
	v_mfma_f32_16x16x32_bf16 v[102:105], v[170:173], v[194:197], v[102:105]
	v_mfma_f32_16x16x32_bf16 v[98:101], v[178:181], v[194:197], v[98:101]
	v_mfma_f32_16x16x32_bf16 v[86:89], v[170:173], v[202:205], v[86:89]
	v_mfma_f32_16x16x32_bf16 v[82:85], v[178:181], v[202:205], v[82:85]
	v_mfma_f32_16x16x32_bf16 v[70:73], v[170:173], v[210:213], v[70:73]
	v_mfma_f32_16x16x32_bf16 v[66:69], v[178:181], v[210:213], v[66:69]
	s_setprio 0
	s_barrier
; #define PG8_STAGE(bufoff, gbase, voff) do { _Pragma("unroll") for (int _i = 0; _i < 2; ++_i) \
;         __builtin_amdgcn_global_load_lds((const unsigned*)((const char*)(gbase) + (voff)[_i]), (LAS unsigned*)(lds + (bufoff) + ldsw + _i * 8192), 16, 0, 0); } while (0)
; #define PG8_LDA(dst, b, h) do { _Pragma("unroll") for (int m = 0; m < 4; ++m) _Pragma("unroll") for (int k = 0; k < 2; ++k) dst[m][k] = *(const LAS bf16x8*)(lds + PG8_SA(b, h) + aoff + m * 2048 + k * 1024); } while (0)
; #define PG8_LDB(dst, b, h) do { _Pragma("unroll") for (int n = 0; n < 2; ++n) _Pragma("unroll") for (int k = 0; k < 2; ++k) dst[n][k] = *(const LAS bf16x8*)(lds + PG8_SB(b, h) + boff + n * 2048 + k * 1024); } while (0)
; #define PG8_MMA(ai, bj, At, Bt) do { __builtin_amdgcn_s_setprio(1); _Pragma("unroll") for (int m = 0; m < 4; ++m) _Pragma("unroll") for (int n = 0; n < 2; ++n) _Pragma("unroll") for (int k = 0; k < 2; ++k) \
;         acc[ai][bj][m][n] = __builtin_amdgcn_mfma_f32_16x16x32_bf16(Bt[n][k], At[m][k], acc[ai][bj][m][n], 0, 0, 0); __builtin_amdgcn_s_setprio(0); } while (0)
; #define PG8_WAIT_V(n) asm volatile("s_waitcnt vmcnt(" #n ")" ::: "memory")
; #define PG8_WAIT_L(n) asm volatile("s_waitcnt lgkmcnt(" #n ")" ::: "memory")
; #define PG8_BAR __builtin_amdgcn_s_barrier()
; #define PG8_SCHED __builtin_amdgcn_sched_barrier(0)
; template <class Epi, int AMODE>
; __device__ __forceinline__ void gemm_phase(LAS unsigned char* lds, const Gemm g, const StaticOrder& S, const Epi& E, int stagger_us, int tid_in) {
;     ...
;             PG8_LDB(B0, 1, 0); PG8_LDB(B1, 1, 1); PG8_SCHED; PG8_LDA(At, 1, 0); PG8_STAGE(PG8_SA(0, 1), a2 + hstepA, voffA);
;             PG8_WAIT_V(8); PG8_WAIT_L(0); PG8_BAR; PG8_MMA(0, 0, At, B0); PG8_MMA(0, 1, At, B1); PG8_BAR; PG8_SCHED;
;             PG8_LDA(At, 1, 1); PG8_STAGE(PG8_SB(1, 0), b3, voffB); PG8_STAGE(PG8_SB(1, 1), b3 + hstepB, voffB); PG8_STAGE(PG8_SA(1, 0), a3, voffA);
;             PG8_WAIT_V(8); PG8_WAIT_L(0); PG8_BAR; PG8_MMA(1, 0, At, B0); PG8_MMA(1, 1, At, B1); PG8_BAR; PG8_SCHED;
;         }
;         if (wr == 0) PG8_BAR;
	s_add_i32 s6, s30, s66
	v_lshl_add_u64 v[140:141], v[140:141], 0, s[74:75]
	s_mov_b32 m0, s6
	ds_read_b128 v[182:185], v164 offset:49152
	ds_read_b128 v[186:189], v164 offset:50176
	ds_read_b128 v[190:193], v164 offset:51200
	ds_read_b128 v[194:197], v164 offset:52224
	ds_read_b128 v[198:201], v164 offset:53248
	ds_read_b128 v[202:205], v164 offset:54272
	ds_read_b128 v[206:209], v164 offset:55296
	ds_read_b128 v[210:213], v164 offset:56320
	global_load_lds_dwordx4 v[140:141], off
	s_add_i32 m0, s6, 0x2000
	s_add_u32 s4, s4, 0x80080
	v_lshl_add_u64 v[140:141], v[160:161], 0, s[74:75]
	s_addc_u32 s5, s5, 0
	s_add_i32 s6, s31, s66
	global_load_lds_dwordx4 v[140:141], off
	v_lshl_add_u64 v[140:141], s[4:5], 0, v[0:1]
	s_mov_b32 m0, s6
	s_nop 0
	global_load_lds_dwordx4 v[140:141], off
	v_lshl_add_u64 v[140:141], s[4:5], 0, v[130:131]
	s_add_i32 m0, s6, 0x2000
	s_nop 0
	global_load_lds_dwordx4 v[140:141], off
	v_lshl_add_u64 v[140:141], v[214:215], 0, s[74:75]
	s_mov_b32 m0, s95
	s_nop 0
	global_load_lds_dwordx4 v[140:141], off
	v_lshl_add_u64 v[140:141], v[216:217], 0, s[74:75]
	s_mov_b32 m0, s96
	s_nop 0
	global_load_lds_dwordx4 v[140:141], off
	s_waitcnt vmcnt(8)
	s_waitcnt lgkmcnt(0)
	s_setprio 1
	s_barrier
	v_mfma_f32_16x16x32_bf16 v[62:65], v[144:147], v[182:185], v[62:65]
	v_mfma_f32_16x16x32_bf16 v[58:61], v[152:155], v[182:185], v[58:61]
	v_mfma_f32_16x16x32_bf16 v[46:49], v[144:147], v[190:193], v[46:49]
	v_mfma_f32_16x16x32_bf16 v[42:45], v[152:155], v[190:193], v[42:45]
	v_mfma_f32_16x16x32_bf16 v[30:33], v[144:147], v[198:201], v[30:33]
	v_mfma_f32_16x16x32_bf16 v[26:29], v[152:155], v[198:201], v[26:29]
	v_mfma_f32_16x16x32_bf16 v[14:17], v[144:147], v[206:209], v[14:17]
	v_mfma_f32_16x16x32_bf16 v[10:13], v[152:155], v[206:209], v[10:13]
	v_mfma_f32_16x16x32_bf16 v[62:65], v[148:151], v[186:189], v[62:65]
	v_mfma_f32_16x16x32_bf16 v[58:61], v[156:159], v[186:189], v[58:61]
	v_mfma_f32_16x16x32_bf16 v[46:49], v[148:151], v[194:197], v[46:49]
	v_mfma_f32_16x16x32_bf16 v[42:45], v[156:159], v[194:197], v[42:45]
	v_mfma_f32_16x16x32_bf16 v[30:33], v[148:151], v[202:205], v[30:33]
	v_mfma_f32_16x16x32_bf16 v[26:29], v[156:159], v[202:205], v[26:29]
	v_mfma_f32_16x16x32_bf16 v[14:17], v[148:151], v[210:213], v[14:17]
	v_mfma_f32_16x16x32_bf16 v[10:13], v[156:159], v[210:213], v[10:13]
	v_mfma_f32_16x16x32_bf16 v[54:57], v[166:169], v[182:185], v[54:57]
	v_mfma_f32_16x16x32_bf16 v[50:53], v[174:177], v[182:185], v[50:53]
	v_mfma_f32_16x16x32_bf16 v[38:41], v[166:169], v[190:193], v[38:41]
	v_mfma_f32_16x16x32_bf16 v[34:37], v[174:177], v[190:193], v[34:37]
	v_mfma_f32_16x16x32_bf16 v[22:25], v[166:169], v[198:201], v[22:25]
	v_mfma_f32_16x16x32_bf16 v[18:21], v[174:177], v[198:201], v[18:21]
	v_mfma_f32_16x16x32_bf16 v[6:9], v[166:169], v[206:209], v[6:9]
	v_mfma_f32_16x16x32_bf16 v[2:5], v[174:177], v[206:209], v[2:5]
	v_mfma_f32_16x16x32_bf16 v[54:57], v[170:173], v[186:189], v[54:57]
	v_mfma_f32_16x16x32_bf16 v[50:53], v[178:181], v[186:189], v[50:53]
	v_mfma_f32_16x16x32_bf16 v[38:41], v[170:173], v[194:197], v[38:41]
	v_mfma_f32_16x16x32_bf16 v[34:37], v[178:181], v[194:197], v[34:37]
	v_mfma_f32_16x16x32_bf16 v[22:25], v[170:173], v[202:205], v[22:25]
	v_mfma_f32_16x16x32_bf16 v[18:21], v[178:181], v[202:205], v[18:21]
	v_mfma_f32_16x16x32_bf16 v[6:9], v[170:173], v[210:213], v[6:9]
	v_mfma_f32_16x16x32_bf16 v[2:5], v[178:181], v[210:213], v[2:5]
	s_setprio 0
	s_barrier
	s_add_i32 s29, s29, 2
	s_add_u32 s60, s60, 0x100
	s_addc_u32 s61, s61, 0
	s_add_u32 vcc_lo, vcc_lo, 0x100
	s_addc_u32 vcc_hi, vcc_hi, 0
	s_cmp_gt_u32 s29, 29
	s_cbranch_scc0 .LBB0_396
	s_and_b64 vcc, exec, s[46:47]
	s_cbranch_vccz .LBB0_399
	s_barrier

; #define PG8_STAGE(bufoff, gbase, voff) do { _Pragma("unroll") for (int _i = 0; _i < 2; ++_i) \
;         __builtin_amdgcn_global_load_lds((const unsigned*)((const char*)(gbase) + (voff)[_i]), (LAS unsigned*)(lds + (bufoff) + ldsw + _i * 8192), 16, 0, 0); } while (0)
; #define PG8_LDA(dst, b, h) do { _Pragma("unroll") for (int m = 0; m < 4; ++m) _Pragma("unroll") for (int k = 0; k < 2; ++k) dst[m][k] = *(const LAS bf16x8*)(lds + PG8_SA(b, h) + aoff + m * 2048 + k * 1024); } while (0)
; #define PG8_WAIT_V(n) asm volatile("s_waitcnt vmcnt(" #n ")" ::: "memory")
; #define PG8_BAR __builtin_amdgcn_s_barrier()
; template <class Epi, int AMODE>
; __device__ __forceinline__ void gemm_phase(LAS unsigned char* lds, const Gemm g, const StaticOrder& S, const Epi& E, int stagger_us, int tid_in) {
;     ...
;         const bool has_next = S.next(ui + 1, nxt);
;         const char* nA = has_next ? Abase + (size_t)nxt.pm * tstepA : cA; const char* nB = has_next ? (const char*)g.Bt + (size_t)nxt.pn * tstepB : cB;
;         for (int t = 0; t < nt; t += 2) {
;             const bool last = (t == nt - 2);
;             const char* a1 = cA + (size_t)(t + 1) * kstep;
;             const char* a2 = last ? nA : cA + (size_t)(t + 2) * kstep; const char* b2 = last ? nB : cB + (size_t)(t + 2) * kstep;
;             const char* a3 = a2 + kstep; const char* b3 = b2 + kstep;
;             PG8_LDB(B0, 0, 0); PG8_LDB(B1, 0, 1); PG8_SCHED; PG8_LDA(At, 0, 0); PG8_STAGE(PG8_SA(1, 1), a1 + hstepA, voffA);
;             PG8_WAIT_V(8); PG8_WAIT_L(0); PG8_BAR; PG8_MMA(0, 0, At, B0); PG8_MMA(0, 1, At, B1); PG8_BAR; PG8_SCHED;
;             PG8_LDA(At, 0, 1); PG8_STAGE(PG8_SB(0, 0), b2, voffB); PG8_STAGE(PG8_SB(0, 1), b2 + hstepB, voffB); PG8_STAGE(PG8_SA(0, 0), a2, voffA);
;             PG8_WAIT_V(8); PG8_WAIT_L(0); PG8_BAR; PG8_MMA(1, 0, At, B0); PG8_MMA(1, 1, At, B1); PG8_BAR; PG8_SCHED;
;             PG8_LDB(B0, 1, 0); PG8_LDB(B1, 1, 1); PG8_SCHED; PG8_LDA(At, 1, 0); PG8_STAGE(PG8_SA(0, 1), a2 + hstepA, voffA);
;             PG8_WAIT_V(8); PG8_WAIT_L(0); PG8_BAR; PG8_MMA(0, 0, At, B0); PG8_MMA(0, 1, At, B1); PG8_BAR; PG8_SCHED;
;             PG8_LDA(At, 1, 1); PG8_STAGE(PG8_SB(1, 0), b3, voffB); PG8_STAGE(PG8_SB(1, 1), b3 + hstepB, voffB); PG8_STAGE(PG8_SA(1, 0), a3, voffA);
;             PG8_WAIT_V(8); PG8_WAIT_L(0); PG8_BAR; PG8_MMA(1, 0, At, B0); PG8_MMA(1, 1, At, B1); PG8_BAR; PG8_SCHED;
.LBB0_1199:
	s_add_u32 s4, s46, 0x100
	s_addc_u32 s5, s47, 0
	s_add_i32 s34, 0, 0x10000
	s_cmp_eq_u32 s31, 28
	s_cselect_b32 s95, s61, s5
	s_cselect_b32 s94, vcc_lo, s4
	s_cselect_b32 s7, s59, s30
	s_cselect_b32 s6, vcc_hi, s29
	s_add_i32 s35, 0, 0x14000
	v_add_u32_e32 v62, s34, v205
	v_add_u32_e32 v158, s35, v205
	ds_read_b128 v[50:53], v62
	ds_read_b128 v[54:57], v62 offset:1024
	ds_read_b128 v[58:61], v62 offset:2048
	ds_read_b128 v[62:65], v62 offset:3072
	ds_read_b128 v[146:149], v158
	ds_read_b128 v[150:153], v158 offset:1024
	ds_read_b128 v[154:157], v158 offset:2048
	ds_read_b128 v[158:161], v158 offset:3072
	v_lshl_add_u64 v[200:201], s[46:47], 0, v[176:177]
	s_add_i32 m0, s66, 0xc000
	ds_read_b128 v[162:165], v207
	ds_read_b128 v[166:169], v207 offset:1024
	ds_read_b128 v[170:173], v207 offset:2048
	ds_read_b128 v[180:183], v207 offset:3072
	ds_read_b128 v[184:187], v207 offset:4096
	ds_read_b128 v[188:191], v207 offset:5120
	ds_read_b128 v[192:195], v207 offset:6144
	ds_read_b128 v[196:199], v207 offset:7168
	global_load_lds_dwordx4 v[200:201], off
	v_lshl_add_u64 v[200:201], s[46:47], 0, v[178:179]
	s_add_i32 m0, s66, 0xe000
	s_nop 0
	global_load_lds_dwordx4 v[200:201], off
	s_waitcnt vmcnt(8)
	s_waitcnt lgkmcnt(0)
	s_setprio 1
	s_barrier
	v_mfma_f32_16x16x32_bf16 v[142:145], v[50:53], v[162:165], v[142:145]
	v_mfma_f32_16x16x32_bf16 v[138:141], v[58:61], v[162:165], v[138:141]
	v_mfma_f32_16x16x32_bf16 v[126:129], v[50:53], v[170:173], v[126:129]
	v_mfma_f32_16x16x32_bf16 v[122:125], v[58:61], v[170:173], v[122:125]
	v_mfma_f32_16x16x32_bf16 v[110:113], v[50:53], v[184:187], v[110:113]
	v_mfma_f32_16x16x32_bf16 v[106:109], v[58:61], v[184:187], v[106:109]
	v_mfma_f32_16x16x32_bf16 v[94:97], v[50:53], v[192:195], v[94:97]
	v_mfma_f32_16x16x32_bf16 v[90:93], v[58:61], v[192:195], v[90:93]
	v_mfma_f32_16x16x32_bf16 v[142:145], v[54:57], v[166:169], v[142:145]
	v_mfma_f32_16x16x32_bf16 v[138:141], v[62:65], v[166:169], v[138:141]
	v_mfma_f32_16x16x32_bf16 v[126:129], v[54:57], v[180:183], v[126:129]
	v_mfma_f32_16x16x32_bf16 v[122:125], v[62:65], v[180:183], v[122:125]
	v_mfma_f32_16x16x32_bf16 v[110:113], v[54:57], v[188:191], v[110:113]
	v_mfma_f32_16x16x32_bf16 v[106:109], v[62:65], v[188:191], v[106:109]
	v_mfma_f32_16x16x32_bf16 v[94:97], v[54:57], v[196:199], v[94:97]
	v_mfma_f32_16x16x32_bf16 v[90:93], v[62:65], v[196:199], v[90:93]
	v_mfma_f32_16x16x32_bf16 v[134:137], v[146:149], v[162:165], v[134:137]
	v_mfma_f32_16x16x32_bf16 v[130:133], v[154:157], v[162:165], v[130:133]
	v_mfma_f32_16x16x32_bf16 v[118:121], v[146:149], v[170:173], v[118:121]
	v_mfma_f32_16x16x32_bf16 v[114:117], v[154:157], v[170:173], v[114:117]
	v_mfma_f32_16x16x32_bf16 v[102:105], v[146:149], v[184:187], v[102:105]
	v_mfma_f32_16x16x32_bf16 v[98:101], v[154:157], v[184:187], v[98:101]
	v_mfma_f32_16x16x32_bf16 v[86:89], v[146:149], v[192:195], v[86:89]
	v_mfma_f32_16x16x32_bf16 v[82:85], v[154:157], v[192:195], v[82:85]
	v_mfma_f32_16x16x32_bf16 v[134:137], v[150:153], v[166:169], v[134:137]
	v_mfma_f32_16x16x32_bf16 v[130:133], v[158:161], v[166:169], v[130:133]
	v_mfma_f32_16x16x32_bf16 v[118:121], v[150:153], v[180:183], v[118:121]
	v_mfma_f32_16x16x32_bf16 v[114:117], v[158:161], v[180:183], v[114:117]
	v_mfma_f32_16x16x32_bf16 v[102:105], v[150:153], v[188:191], v[102:105]
	v_mfma_f32_16x16x32_bf16 v[98:101], v[158:161], v[188:191], v[98:101]
	v_mfma_f32_16x16x32_bf16 v[86:89], v[150:153], v[196:199], v[86:89]
	v_mfma_f32_16x16x32_bf16 v[82:85], v[158:161], v[196:199], v[82:85]
	s_setprio 0
	s_barrier
	s_add_i32 s34, s34, s13
	v_lshl_add_u64 v[200:201], s[6:7], 0, v[0:1]
	s_mov_b32 m0, s34
	ds_read_b128 v[162:165], v207 offset:16384
	ds_read_b128 v[166:169], v207 offset:17408
	ds_read_b128 v[170:173], v207 offset:18432
	ds_read_b128 v[180:183], v207 offset:19456
	ds_read_b128 v[184:187], v207 offset:20480
	ds_read_b128 v[188:191], v207 offset:21504
	ds_read_b128 v[192:195], v207 offset:22528
	ds_read_b128 v[196:199], v207 offset:23552
	global_load_lds_dwordx4 v[200:201], off
	s_add_i32 m0, s34, 0x2000
	s_add_u32 s46, s6, 0x80000
	v_lshl_add_u64 v[202:203], s[6:7], 0, v[174:175]
	s_addc_u32 s47, s7, 0
	s_add_i32 s34, s35, s13
	global_load_lds_dwordx4 v[202:203], off
	v_lshl_add_u64 v[208:209], s[46:47], 0, v[0:1]
	s_mov_b32 m0, s34
	v_lshl_add_u64 v[210:211], s[94:95], 0, v[174:175]
	global_load_lds_dwordx4 v[208:209], off
	v_lshl_add_u64 v[208:209], s[46:47], 0, v[174:175]
	s_add_i32 m0, s34, 0x2000
	s_nop 0
	global_load_lds_dwordx4 v[208:209], off
	v_lshl_add_u64 v[208:209], s[94:95], 0, v[0:1]
	s_mov_b32 m0, s66
	s_nop 0
	global_load_lds_dwordx4 v[208:209], off
	s_mov_b32 m0, s67
	s_nop 0
	global_load_lds_dwordx4 v[210:211], off
	s_waitcnt vmcnt(8)
	s_waitcnt lgkmcnt(0)
	s_setprio 1
	s_barrier
; #define PG8_STAGE(bufoff, gbase, voff) do { _Pragma("unroll") for (int _i = 0; _i < 2; ++_i) \
;         __builtin_amdgcn_global_load_lds((const unsigned*)((const char*)(gbase) + (voff)[_i]), (LAS unsigned*)(lds + (bufoff) + ldsw + _i * 8192), 16, 0, 0); } while (0)
; #define PG8_LDA(dst, b, h) do { _Pragma("unroll") for (int m = 0; m < 4; ++m) _Pragma("unroll") for (int k = 0; k < 2; ++k) dst[m][k] = *(const LAS bf16x8*)(lds + PG8_SA(b, h) + aoff + m * 2048 + k * 1024); } while (0)
; #define PG8_LDB(dst, b, h) do { _Pragma("unroll") for (int n = 0; n < 2; ++n) _Pragma("unroll") for (int k = 0; k < 2; ++k) dst[n][k] = *(const LAS bf16x8*)(lds + PG8_SB(b, h) + boff + n * 2048 + k * 1024); } while (0)
; #define PG8_MMA(ai, bj, At, Bt) do { __builtin_amdgcn_s_setprio(1); _Pragma("unroll") for (int m = 0; m < 4; ++m) _Pragma("unroll") for (int n = 0; n < 2; ++n) _Pragma("unroll") for (int k = 0; k < 2; ++k) \
;         acc[ai][bj][m][n] = __builtin_amdgcn_mfma_f32_16x16x32_bf16(Bt[n][k], At[m][k], acc[ai][bj][m][n], 0, 0, 0); __builtin_amdgcn_s_setprio(0); } while (0)
; #define PG8_WAIT_V(n) asm volatile("s_waitcnt vmcnt(" #n ")" ::: "memory")
; template <class Epi, int AMODE>
; __device__ __forceinline__ void gemm_phase(LAS unsigned char* lds, const Gemm g, const StaticOrder& S, const Epi& E, int stagger_us, int tid_in) {
;     ...
;             PG8_LDB(B0, 0, 0); PG8_LDB(B1, 0, 1); PG8_SCHED; PG8_LDA(At, 0, 0); PG8_STAGE(PG8_SA(1, 1), a1 + hstepA, voffA);
;             PG8_WAIT_V(8); PG8_WAIT_L(0); PG8_BAR; PG8_MMA(0, 0, At, B0); PG8_MMA(0, 1, At, B1); PG8_BAR; PG8_SCHED;
;             PG8_LDA(At, 0, 1); PG8_STAGE(PG8_SB(0, 0), b2, voffB); PG8_STAGE(PG8_SB(0, 1), b2 + hstepB, voffB); PG8_STAGE(PG8_SA(0, 0), a2, voffA);
;             PG8_WAIT_V(8); PG8_WAIT_L(0); PG8_BAR; PG8_MMA(1, 0, At, B0); PG8_MMA(1, 1, At, B1); PG8_BAR; PG8_SCHED;
;             PG8_LDB(B0, 1, 0); PG8_LDB(B1, 1, 1); PG8_SCHED; PG8_LDA(At, 1, 0); PG8_STAGE(PG8_SA(0, 1), a2 + hstepA, voffA);
;             PG8_WAIT_V(8); PG8_WAIT_L(0); PG8_BAR; PG8_MMA(0, 0, At, B0); PG8_MMA(0, 1, At, B1); PG8_BAR; PG8_SCHED;
;             PG8_LDA(At, 1, 1); PG8_STAGE(PG8_SB(1, 0), b3, voffB); PG8_STAGE(PG8_SB(1, 1), b3 + hstepB, voffB); PG8_STAGE(PG8_SA(1, 0), a3, voffA);
;             PG8_WAIT_V(8); PG8_WAIT_L(0); PG8_BAR; PG8_MMA(1, 0, At, B0); PG8_MMA(1, 1, At, B1); PG8_BAR; PG8_SCHED;
	v_mfma_f32_16x16x32_bf16 v[78:81], v[50:53], v[162:165], v[78:81]
	v_mfma_f32_16x16x32_bf16 v[74:77], v[58:61], v[162:165], v[74:77]
	v_mfma_f32_16x16x32_bf16 v[46:49], v[50:53], v[170:173], v[46:49]
	v_mfma_f32_16x16x32_bf16 v[42:45], v[58:61], v[170:173], v[42:45]
	v_mfma_f32_16x16x32_bf16 v[30:33], v[50:53], v[184:187], v[30:33]
	v_mfma_f32_16x16x32_bf16 v[26:29], v[58:61], v[184:187], v[26:29]
	v_mfma_f32_16x16x32_bf16 v[14:17], v[50:53], v[192:195], v[14:17]
	v_mfma_f32_16x16x32_bf16 v[10:13], v[58:61], v[192:195], v[10:13]
	v_mfma_f32_16x16x32_bf16 v[78:81], v[54:57], v[166:169], v[78:81]
	v_mfma_f32_16x16x32_bf16 v[74:77], v[62:65], v[166:169], v[74:77]
	v_mfma_f32_16x16x32_bf16 v[46:49], v[54:57], v[180:183], v[46:49]
	v_mfma_f32_16x16x32_bf16 v[42:45], v[62:65], v[180:183], v[42:45]
	v_mfma_f32_16x16x32_bf16 v[30:33], v[54:57], v[188:191], v[30:33]
	v_mfma_f32_16x16x32_bf16 v[26:29], v[62:65], v[188:191], v[26:29]
	v_mfma_f32_16x16x32_bf16 v[14:17], v[54:57], v[196:199], v[14:17]
	v_mfma_f32_16x16x32_bf16 v[10:13], v[62:65], v[196:199], v[10:13]
	v_mfma_f32_16x16x32_bf16 v[38:41], v[146:149], v[170:173], v[38:41]
	v_mfma_f32_16x16x32_bf16 v[34:37], v[154:157], v[170:173], v[34:37]
	v_mfma_f32_16x16x32_bf16 v[22:25], v[146:149], v[184:187], v[22:25]
	v_mfma_f32_16x16x32_bf16 v[18:21], v[154:157], v[184:187], v[18:21]
	v_mfma_f32_16x16x32_bf16 v[6:9], v[146:149], v[192:195], v[6:9]
	v_mfma_f32_16x16x32_bf16 v[2:5], v[154:157], v[192:195], v[2:5]
	v_mfma_f32_16x16x32_bf16 v[50:53], v[146:149], v[162:165], v[70:73]
	v_mfma_f32_16x16x32_bf16 v[54:57], v[154:157], v[162:165], v[66:69]
	v_mfma_f32_16x16x32_bf16 v[38:41], v[150:153], v[180:183], v[38:41]
	v_mfma_f32_16x16x32_bf16 v[34:37], v[158:161], v[180:183], v[34:37]
	v_mfma_f32_16x16x32_bf16 v[22:25], v[150:153], v[188:191], v[22:25]
	v_mfma_f32_16x16x32_bf16 v[18:21], v[158:161], v[188:191], v[18:21]
	v_mfma_f32_16x16x32_bf16 v[6:9], v[150:153], v[196:199], v[6:9]
	v_mfma_f32_16x16x32_bf16 v[2:5], v[158:161], v[196:199], v[2:5]
	v_mfma_f32_16x16x32_bf16 v[50:53], v[150:153], v[166:169], v[50:53]
	v_mfma_f32_16x16x32_bf16 v[54:57], v[158:161], v[166:169], v[54:57]
	s_setprio 0
	s_barrier
	s_add_i32 s34, 0, 0x18000
	s_add_i32 s35, 0, 0x1c000
	v_add_u32_e32 v70, s34, v205
	v_add_u32_e32 v158, s35, v205
	ds_read_b128 v[58:61], v70
	ds_read_b128 v[62:65], v70 offset:1024
	ds_read_b128 v[66:69], v70 offset:2048
	ds_read_b128 v[70:73], v70 offset:3072
	ds_read_b128 v[146:149], v158
	ds_read_b128 v[150:153], v158 offset:1024
	ds_read_b128 v[154:157], v158 offset:2048
	ds_read_b128 v[158:161], v158 offset:3072
	s_add_u32 s46, s94, 0x80000
	s_addc_u32 s47, s95, 0
	s_mov_b32 m0, s69
	v_lshl_add_u64 v[212:213], s[46:47], 0, v[0:1]
	ds_read_b128 v[162:165], v207 offset:32768
	ds_read_b128 v[166:169], v207 offset:33792
	ds_read_b128 v[170:173], v207 offset:34816
	ds_read_b128 v[180:183], v207 offset:35840
	ds_read_b128 v[184:187], v207 offset:36864
	ds_read_b128 v[188:191], v207 offset:37888
	ds_read_b128 v[192:195], v207 offset:38912
	ds_read_b128 v[196:199], v207 offset:39936
	global_load_lds_dwordx4 v[212:213], off
	v_lshl_add_u64 v[212:213], s[46:47], 0, v[174:175]
	s_mov_b32 m0, s72
	s_nop 0
	global_load_lds_dwordx4 v[212:213], off
	s_waitcnt vmcnt(8)
	s_waitcnt lgkmcnt(0)
	s_setprio 1
	s_barrier
	v_mfma_f32_16x16x32_bf16 v[142:145], v[58:61], v[162:165], v[142:145]
	v_mfma_f32_16x16x32_bf16 v[138:141], v[66:69], v[162:165], v[138:141]
	v_mfma_f32_16x16x32_bf16 v[126:129], v[58:61], v[170:173], v[126:129]
	v_mfma_f32_16x16x32_bf16 v[122:125], v[66:69], v[170:173], v[122:125]
	v_mfma_f32_16x16x32_bf16 v[110:113], v[58:61], v[184:187], v[110:113]
	v_mfma_f32_16x16x32_bf16 v[106:109], v[66:69], v[184:187], v[106:109]
	v_mfma_f32_16x16x32_bf16 v[94:97], v[58:61], v[192:195], v[94:97]
	v_mfma_f32_16x16x32_bf16 v[90:93], v[66:69], v[192:195], v[90:93]
	v_mfma_f32_16x16x32_bf16 v[142:145], v[62:65], v[166:169], v[142:145]
	v_mfma_f32_16x16x32_bf16 v[138:141], v[70:73], v[166:169], v[138:141]
	v_mfma_f32_16x16x32_bf16 v[126:129], v[62:65], v[180:183], v[126:129]
	v_mfma_f32_16x16x32_bf16 v[122:125], v[70:73], v[180:183], v[122:125]
	v_mfma_f32_16x16x32_bf16 v[110:113], v[62:65], v[188:191], v[110:113]
	v_mfma_f32_16x16x32_bf16 v[106:109], v[70:73], v[188:191], v[106:109]
	v_mfma_f32_16x16x32_bf16 v[94:97], v[62:65], v[196:199], v[94:97]
	v_mfma_f32_16x16x32_bf16 v[90:93], v[70:73], v[196:199], v[90:93]
	v_mfma_f32_16x16x32_bf16 v[134:137], v[146:149], v[162:165], v[134:137]
	v_mfma_f32_16x16x32_bf16 v[130:133], v[154:157], v[162:165], v[130:133]
	v_mfma_f32_16x16x32_bf16 v[118:121], v[146:149], v[170:173], v[118:121]
	v_mfma_f32_16x16x32_bf16 v[114:117], v[154:157], v[170:173], v[114:117]
	v_mfma_f32_16x16x32_bf16 v[102:105], v[146:149], v[184:187], v[102:105]
	v_mfma_f32_16x16x32_bf16 v[98:101], v[154:157], v[184:187], v[98:101]
	v_mfma_f32_16x16x32_bf16 v[86:89], v[146:149], v[192:195], v[86:89]
	v_mfma_f32_16x16x32_bf16 v[82:85], v[154:157], v[192:195], v[82:85]
	v_mfma_f32_16x16x32_bf16 v[134:137], v[150:153], v[166:169], v[134:137]
	v_mfma_f32_16x16x32_bf16 v[130:133], v[158:161], v[166:169], v[130:133]
	v_mfma_f32_16x16x32_bf16 v[118:121], v[150:153], v[180:183], v[118:121]
	v_mfma_f32_16x16x32_bf16 v[114:117], v[158:161], v[180:183], v[114:117]
	v_mfma_f32_16x16x32_bf16 v[102:105], v[150:153], v[188:191], v[102:105]
	v_mfma_f32_16x16x32_bf16 v[98:101], v[158:161], v[188:191], v[98:101]
	v_mfma_f32_16x16x32_bf16 v[86:89], v[150:153], v[196:199], v[86:89]
	v_mfma_f32_16x16x32_bf16 v[82:85], v[158:161], v[196:199], v[82:85]
	s_setprio 0
	s_barrier
; #define PG8_STAGE(bufoff, gbase, voff) do { _Pragma("unroll") for (int _i = 0; _i < 2; ++_i) \
;         __builtin_amdgcn_global_load_lds((const unsigned*)((const char*)(gbase) + (voff)[_i]), (LAS unsigned*)(lds + (bufoff) + ldsw + _i * 8192), 16, 0, 0); } while (0)
; #define PG8_LDA(dst, b, h) do { _Pragma("unroll") for (int m = 0; m < 4; ++m) _Pragma("unroll") for (int k = 0; k < 2; ++k) dst[m][k] = *(const LAS bf16x8*)(lds + PG8_SA(b, h) + aoff + m * 2048 + k * 1024); } while (0)
; #define PG8_LDB(dst, b, h) do { _Pragma("unroll") for (int n = 0; n < 2; ++n) _Pragma("unroll") for (int k = 0; k < 2; ++k) dst[n][k] = *(const LAS bf16x8*)(lds + PG8_SB(b, h) + boff + n * 2048 + k * 1024); } while (0)
; #define PG8_MMA(ai, bj, At, Bt) do { __builtin_amdgcn_s_setprio(1); _Pragma("unroll") for (int m = 0; m < 4; ++m) _Pragma("unroll") for (int n = 0; n < 2; ++n) _Pragma("unroll") for (int k = 0; k < 2; ++k) \
;         acc[ai][bj][m][n] = __builtin_amdgcn_mfma_f32_16x16x32_bf16(Bt[n][k], At[m][k], acc[ai][bj][m][n], 0, 0, 0); __builtin_amdgcn_s_setprio(0); } while (0)
; #define PG8_WAIT_V(n) asm volatile("s_waitcnt vmcnt(" #n ")" ::: "memory")
; #define PG8_WAIT_L(n) asm volatile("s_waitcnt lgkmcnt(" #n ")" ::: "memory")
; #define PG8_BAR __builtin_amdgcn_s_barrier()
; #define PG8_SCHED __builtin_amdgcn_sched_barrier(0)
; template <class Epi, int AMODE>
; __device__ __forceinline__ void gemm_phase(LAS unsigned char* lds, const Gemm g, const StaticOrder& S, const Epi& E, int stagger_us, int tid_in) {
;     ...
;             PG8_LDB(B0, 1, 0); PG8_LDB(B1, 1, 1); PG8_SCHED; PG8_LDA(At, 1, 0); PG8_STAGE(PG8_SA(0, 1), a2 + hstepA, voffA);
;             PG8_WAIT_V(8); PG8_WAIT_L(0); PG8_BAR; PG8_MMA(0, 0, At, B0); PG8_MMA(0, 1, At, B1); PG8_BAR; PG8_SCHED;
;             PG8_LDA(At, 1, 1); PG8_STAGE(PG8_SB(1, 0), b3, voffB); PG8_STAGE(PG8_SB(1, 1), b3 + hstepB, voffB); PG8_STAGE(PG8_SA(1, 0), a3, voffA);
;             PG8_WAIT_V(8); PG8_WAIT_L(0); PG8_BAR; PG8_MMA(1, 0, At, B0); PG8_MMA(1, 1, At, B1); PG8_BAR; PG8_SCHED;
;         }
;         if (wr == 0) PG8_BAR;
	s_add_i32 s34, s34, s13
	v_lshl_add_u64 v[200:201], v[200:201], 0, s[74:75]
	s_mov_b32 m0, s34
	ds_read_b128 v[162:165], v207 offset:49152
	ds_read_b128 v[166:169], v207 offset:50176
	ds_read_b128 v[170:173], v207 offset:51200
	ds_read_b128 v[180:183], v207 offset:52224
	ds_read_b128 v[184:187], v207 offset:53248
	ds_read_b128 v[188:191], v207 offset:54272
	ds_read_b128 v[192:195], v207 offset:55296
	ds_read_b128 v[196:199], v207 offset:56320
	global_load_lds_dwordx4 v[200:201], off
	s_add_i32 m0, s34, 0x2000
	s_add_u32 s6, s6, 0x80080
	v_lshl_add_u64 v[200:201], v[202:203], 0, s[74:75]
	s_addc_u32 s7, s7, 0
	s_add_i32 s34, s35, s13
	global_load_lds_dwordx4 v[200:201], off
	v_lshl_add_u64 v[200:201], s[6:7], 0, v[0:1]
	s_mov_b32 m0, s34
	s_nop 0
	global_load_lds_dwordx4 v[200:201], off
	v_lshl_add_u64 v[200:201], s[6:7], 0, v[174:175]
	s_add_i32 m0, s34, 0x2000
	s_nop 0
	global_load_lds_dwordx4 v[200:201], off
	v_lshl_add_u64 v[200:201], v[208:209], 0, s[74:75]
	s_mov_b32 m0, s91
	s_nop 0
	global_load_lds_dwordx4 v[200:201], off
	v_lshl_add_u64 v[200:201], v[210:211], 0, s[74:75]
	s_mov_b32 m0, s96
	s_nop 0
	global_load_lds_dwordx4 v[200:201], off
	s_waitcnt vmcnt(8)
	s_waitcnt lgkmcnt(0)
	s_setprio 1
	s_barrier
	v_mfma_f32_16x16x32_bf16 v[78:81], v[58:61], v[162:165], v[78:81]
	v_mfma_f32_16x16x32_bf16 v[74:77], v[66:69], v[162:165], v[74:77]
	v_mfma_f32_16x16x32_bf16 v[46:49], v[58:61], v[170:173], v[46:49]
	v_mfma_f32_16x16x32_bf16 v[42:45], v[66:69], v[170:173], v[42:45]
	v_mfma_f32_16x16x32_bf16 v[30:33], v[58:61], v[184:187], v[30:33]
	v_mfma_f32_16x16x32_bf16 v[26:29], v[66:69], v[184:187], v[26:29]
	v_mfma_f32_16x16x32_bf16 v[14:17], v[58:61], v[192:195], v[14:17]
	v_mfma_f32_16x16x32_bf16 v[10:13], v[66:69], v[192:195], v[10:13]
	v_mfma_f32_16x16x32_bf16 v[78:81], v[62:65], v[166:169], v[78:81]
	v_mfma_f32_16x16x32_bf16 v[74:77], v[70:73], v[166:169], v[74:77]
	v_mfma_f32_16x16x32_bf16 v[46:49], v[62:65], v[180:183], v[46:49]
	v_mfma_f32_16x16x32_bf16 v[42:45], v[70:73], v[180:183], v[42:45]
	v_mfma_f32_16x16x32_bf16 v[30:33], v[62:65], v[188:191], v[30:33]
	v_mfma_f32_16x16x32_bf16 v[26:29], v[70:73], v[188:191], v[26:29]
	v_mfma_f32_16x16x32_bf16 v[14:17], v[62:65], v[196:199], v[14:17]
	v_mfma_f32_16x16x32_bf16 v[10:13], v[70:73], v[196:199], v[10:13]
	v_mfma_f32_16x16x32_bf16 v[50:53], v[146:149], v[162:165], v[50:53]
	v_mfma_f32_16x16x32_bf16 v[70:73], v[150:153], v[166:169], v[50:53]
	v_mfma_f32_16x16x32_bf16 v[50:53], v[154:157], v[162:165], v[54:57]
	v_mfma_f32_16x16x32_bf16 v[38:41], v[146:149], v[170:173], v[38:41]
	v_mfma_f32_16x16x32_bf16 v[34:37], v[154:157], v[170:173], v[34:37]
	v_mfma_f32_16x16x32_bf16 v[22:25], v[146:149], v[184:187], v[22:25]
	v_mfma_f32_16x16x32_bf16 v[18:21], v[154:157], v[184:187], v[18:21]
	v_mfma_f32_16x16x32_bf16 v[6:9], v[146:149], v[192:195], v[6:9]
	v_mfma_f32_16x16x32_bf16 v[2:5], v[154:157], v[192:195], v[2:5]
	v_mfma_f32_16x16x32_bf16 v[66:69], v[158:161], v[166:169], v[50:53]
	v_mfma_f32_16x16x32_bf16 v[38:41], v[150:153], v[180:183], v[38:41]
	v_mfma_f32_16x16x32_bf16 v[34:37], v[158:161], v[180:183], v[34:37]
	v_mfma_f32_16x16x32_bf16 v[22:25], v[150:153], v[188:191], v[22:25]
	v_mfma_f32_16x16x32_bf16 v[18:21], v[158:161], v[188:191], v[18:21]
	v_mfma_f32_16x16x32_bf16 v[6:9], v[150:153], v[196:199], v[6:9]
	v_mfma_f32_16x16x32_bf16 v[2:5], v[158:161], v[196:199], v[2:5]
	s_setprio 0
	s_barrier
	s_add_i32 s31, s31, 2
	s_add_u32 s29, s29, 0x100
	s_addc_u32 s30, s30, 0
	s_cmp_gt_u32 s31, 29
	s_mov_b64 s[46:47], s[4:5]
	s_cbranch_scc0 .LBB0_1199
	s_and_b64 vcc, exec, s[56:57]
	s_cbranch_vccz .LBB0_1202
	s_barrier

; #define PG8_STAGE(bufoff, gbase, voff) do { _Pragma("unroll") for (int _i = 0; _i < 2; ++_i) \
;         __builtin_amdgcn_global_load_lds((const unsigned*)((const char*)(gbase) + (voff)[_i]), (LAS unsigned*)(lds + (bufoff) + ldsw + _i * 8192), 16, 0, 0); } while (0)
; #define PG8_LDA(dst, b, h) do { _Pragma("unroll") for (int m = 0; m < 4; ++m) _Pragma("unroll") for (int k = 0; k < 2; ++k) dst[m][k] = *(const LAS bf16x8*)(lds + PG8_SA(b, h) + aoff + m * 2048 + k * 1024); } while (0)
; #define PG8_BAR __builtin_amdgcn_s_barrier()
; template <class Epi, int AMODE>
; __device__ __forceinline__ void gemm_phase(LAS unsigned char* lds, const Gemm g, const StaticOrder& S, const Epi& E, int stagger_us, int tid_in) {
;     ...
;         const bool has_next = S.next(ui + 1, nxt);
;         const char* nA = has_next ? Abase + (size_t)nxt.pm * tstepA : cA; const char* nB = has_next ? (const char*)g.Bt + (size_t)nxt.pn * tstepB : cB;
;         for (int t = 0; t < nt; t += 2) {
;             const bool last = (t == nt - 2);
;             const char* a1 = cA + (size_t)(t + 1) * kstep;
;             const char* a2 = last ? nA : cA + (size_t)(t + 2) * kstep; const char* b2 = last ? nB : cB + (size_t)(t + 2) * kstep;
;             const char* a3 = a2 + kstep; const char* b3 = b2 + kstep;
;             PG8_LDB(B0, 0, 0); PG8_LDB(B1, 0, 1); PG8_SCHED; PG8_LDA(At, 0, 0); PG8_STAGE(PG8_SA(1, 1), a1 + hstepA, voffA);
;             PG8_WAIT_V(8); PG8_WAIT_L(0); PG8_BAR; PG8_MMA(0, 0, At, B0); PG8_MMA(0, 1, At, B1); PG8_BAR; PG8_SCHED;
;     __device__ __forceinline__ void operator()(f32x4 (&acc)[2][2][4][2], const Unit& u, int wr, int wc, int fr, int fq) const {
;     ...
;             const int tq = tok0 + 8 * fr; const int tA = tq < 0 ? 0 : (tq > TOK - 1 ? TOK - 1 : tq), tB = (tq + 7) > TOK - 1 ? TOK - 1 : (tq + 7);
;             const int bA = batch_of(tA), bB = batch_of(tB); const bool same = __all(bA == bB);
;             const float* bp0 = bias + 256 * u.pn + 32 * wc + 8 * fq;
;             f32x4 bvA[2][2]; float sq[8];
; #pragma unroll
;             for (int am = 0; am < 8; ++am) { int tok = tq + am; tok = tok < 0 ? 0 : (tok > TOK - 1 ? TOK - 1 : tok); sq[am] = LDG(float, ssq + tok); }
; #pragma unroll
;             for (int bj = 0; bj < 2; ++bj)
; #pragma unroll
;                 for (int n = 0; n < 2; ++n) bvA[bj][n] = LDG(f32x4, bp0 + (size_t)bA * (2 * DFF) + bj * HALF + 4 * n);
.LBB0_1298:
	s_ashr_i32 s47, s46, 31
	s_lshl_b64 s[6:7], s[46:47], 20
	s_add_u32 s96, s9, s6
	s_addc_u32 s97, s72, s7
	s_and_b64 s[6:7], s[42:43], exec
	s_cselect_b32 s27, s97, s5
	s_cselect_b32 s28, s96, s4
	s_add_u32 s29, s4, 0x100
	v_mov_b32_e32 v2, 0
	s_addc_u32 s30, s5, 0
	s_mov_b32 s31, -2
	s_mul_i32 s6, s26, 0xfc
	v_add_u32_e32 v222, s6, v197
	v_med3_i32 v240, v222, 0, v238
	v_add_u32_e32 v241, 0xffffe000, v240
	v_lshrrev_b32_e32 v241, 12, v241
	v_add_u32_e32 v241, 4, v241
	v_lshrrev_b32_e32 v242, 11, v240
	v_mov_b32_e32 v243, 0x2000
	v_cmp_gt_i32_e64 s[6:7], v243, v222
	s_nop 1
	v_cndmask_b32_e64 v241, v241, v242, s[6:7]
	s_lshl_b32 s6, s92, 8
	s_ashr_i32 s7, s6, 31
	v_lshl_add_u64 v[236:237], s[6:7], 2, v[184:185]
	v_mad_u64_u32 v[236:237], s[6:7], v241, s15, v[236:237]
	v_med3_i32 v224, v222, 0, v238
	v_lshlrev_b32_e32 v224, 2, v224
	global_load_dword v224, v224, s[56:57]
	v_add_u32_e32 v228, 1, v222
	v_med3_i32 v228, v228, 0, v238
	v_lshlrev_b32_e32 v228, 2, v228
	global_load_dword v228, v228, s[56:57]
	v_add_u32_e32 v231, 2, v222
	v_med3_i32 v231, v231, 0, v238
	v_lshlrev_b32_e32 v231, 2, v231
	global_load_dword v231, v231, s[56:57]
	v_add_u32_e32 v233, 3, v222
	v_med3_i32 v233, v233, 0, v238
	v_lshlrev_b32_e32 v233, 2, v233
	global_load_dword v233, v233, s[56:57]
	v_add_u32_e32 v234, 4, v222
	v_med3_i32 v234, v234, 0, v238
	v_lshlrev_b32_e32 v234, 2, v234
	global_load_dword v234, v234, s[56:57]
	v_add_u32_e32 v239, 5, v222
	v_med3_i32 v239, v239, 0, v238
	v_lshlrev_b32_e32 v239, 2, v239
	global_load_dword v239, v239, s[56:57]
	v_add_u32_e32 v252, 6, v222
	v_med3_i32 v252, v252, 0, v238
	v_lshlrev_b32_e32 v252, 2, v252
	global_load_dword v252, v252, s[56:57]
	v_add_u32_e32 v253, 7, v222
	v_med3_i32 v253, v253, 0, v238
	v_lshlrev_b32_e32 v253, 2, v253
	global_load_dword v253, v253, s[56:57]
	global_load_dwordx4 v[240:243], v[236:237], off
	global_load_dwordx4 v[244:247], v[236:237], off offset:16
	global_load_dwordx4 v[248:251], v[236:237], off offset:512
	global_load_dwordx2 v[222:223], v[236:237], off offset:528
	s_nop 0
	global_load_dwordx2 v[236:237], v[236:237], off offset:536
	v_mov_b32_e32 v3, v2
	v_mov_b32_e32 v4, v2
	v_mov_b32_e32 v5, v2
	v_mov_b32_e32 v14, v2
	v_mov_b32_e32 v15, v2
	v_mov_b32_e32 v16, v2
	v_mov_b32_e32 v17, v2
	v_mov_b32_e32 v10, v2
	v_mov_b32_e32 v11, v2
	v_mov_b32_e32 v12, v2
	v_mov_b32_e32 v13, v2
	v_mov_b32_e32 v26, v2
	v_mov_b32_e32 v27, v2
	v_mov_b32_e32 v28, v2
	v_mov_b32_e32 v29, v2
	v_mov_b32_e32 v6, v2
	v_mov_b32_e32 v7, v2
	v_mov_b32_e32 v8, v2
	v_mov_b32_e32 v9, v2
	v_mov_b32_e32 v42, v2
	v_mov_b32_e32 v43, v2
	v_mov_b32_e32 v44, v2
	v_mov_b32_e32 v45, v2
	v_mov_b32_e32 v30, v2
	v_mov_b32_e32 v31, v2
	v_mov_b32_e32 v32, v2
	v_mov_b32_e32 v33, v2
	v_mov_b32_e32 v58, v2
	v_mov_b32_e32 v59, v2
	v_mov_b32_e32 v60, v2
	v_mov_b32_e32 v61, v2
	v_mov_b32_e32 v74, v2
	v_mov_b32_e32 v75, v2
	v_mov_b32_e32 v76, v2
	v_mov_b32_e32 v77, v2
	v_mov_b32_e32 v22, v2
	v_mov_b32_e32 v23, v2
	v_mov_b32_e32 v24, v2
	v_mov_b32_e32 v25, v2
	v_mov_b32_e32 v34, v2
	v_mov_b32_e32 v35, v2
	v_mov_b32_e32 v36, v2
	v_mov_b32_e32 v37, v2
	v_mov_b32_e32 v18, v2
	v_mov_b32_e32 v19, v2
	v_mov_b32_e32 v20, v2
	v_mov_b32_e32 v21, v2
	v_mov_b32_e32 v50, v2
	v_mov_b32_e32 v51, v2
	v_mov_b32_e32 v52, v2
	v_mov_b32_e32 v53, v2
	v_mov_b32_e32 v38, v2
	v_mov_b32_e32 v39, v2
	v_mov_b32_e32 v40, v2
	v_mov_b32_e32 v41, v2
	v_mov_b32_e32 v46, v2
	v_mov_b32_e32 v47, v2
	v_mov_b32_e32 v48, v2
	v_mov_b32_e32 v49, v2
	v_mov_b32_e32 v54, v2
	v_mov_b32_e32 v55, v2
	v_mov_b32_e32 v56, v2
	v_mov_b32_e32 v57, v2
	v_mov_b32_e32 v66, v2
	v_mov_b32_e32 v67, v2
	v_mov_b32_e32 v68, v2
	v_mov_b32_e32 v69, v2
	v_mov_b32_e32 v78, v2
	v_mov_b32_e32 v79, v2
	v_mov_b32_e32 v80, v2
	v_mov_b32_e32 v81, v2
	v_mov_b32_e32 v62, v2
	v_mov_b32_e32 v63, v2
	v_mov_b32_e32 v64, v2
	v_mov_b32_e32 v65, v2
	v_mov_b32_e32 v70, v2
	v_mov_b32_e32 v71, v2
	v_mov_b32_e32 v72, v2
	v_mov_b32_e32 v73, v2
	v_mov_b32_e32 v86, v2
	v_mov_b32_e32 v87, v2
	v_mov_b32_e32 v88, v2
	v_mov_b32_e32 v89, v2
	v_mov_b32_e32 v94, v2
	v_mov_b32_e32 v95, v2
	v_mov_b32_e32 v96, v2
	v_mov_b32_e32 v97, v2
	v_mov_b32_e32 v98, v2
	v_mov_b32_e32 v99, v2
	v_mov_b32_e32 v100, v2
	v_mov_b32_e32 v101, v2
	v_mov_b32_e32 v106, v2
	v_mov_b32_e32 v107, v2
	v_mov_b32_e32 v108, v2
	v_mov_b32_e32 v109, v2
	v_mov_b32_e32 v82, v2
	v_mov_b32_e32 v83, v2
	v_mov_b32_e32 v84, v2
	v_mov_b32_e32 v85, v2
	v_mov_b32_e32 v90, v2
	v_mov_b32_e32 v91, v2
	v_mov_b32_e32 v92, v2
	v_mov_b32_e32 v93, v2
	v_mov_b32_e32 v102, v2
	v_mov_b32_e32 v103, v2
	v_mov_b32_e32 v104, v2
	v_mov_b32_e32 v105, v2
	v_mov_b32_e32 v110, v2
	v_mov_b32_e32 v111, v2
	v_mov_b32_e32 v112, v2
	v_mov_b32_e32 v113, v2
	v_mov_b32_e32 v114, v2
	v_mov_b32_e32 v115, v2
	v_mov_b32_e32 v116, v2
	v_mov_b32_e32 v117, v2
	v_mov_b32_e32 v118, v2
	v_mov_b32_e32 v119, v2
	v_mov_b32_e32 v120, v2
	v_mov_b32_e32 v121, v2
	v_mov_b32_e32 v122, v2
	v_mov_b32_e32 v123, v2
	v_mov_b32_e32 v124, v2
	v_mov_b32_e32 v125, v2
	v_mov_b32_e32 v126, v2
	v_mov_b32_e32 v127, v2
	v_mov_b32_e32 v128, v2
	v_mov_b32_e32 v129, v2
	s_add_u32 s4, s44, 0x100
	s_addc_u32 s5, s45, 0
	s_add_i32 s34, 0, 0x10000
	s_cmp_eq_u32 s31, 28
	s_cselect_b32 s43, s95, s5
	s_cselect_b32 s42, s94, s4
	s_cselect_b32 s7, s27, s30
	s_cselect_b32 s6, s28, s29
	s_add_i32 s35, 0, 0x14000
	v_add_u32_e32 v142, s34, v196
	v_add_u32_e32 v158, s35, v196
	ds_read_b128 v[130:133], v142
	ds_read_b128 v[134:137], v142 offset:1024
	ds_read_b128 v[138:141], v142 offset:2048
	ds_read_b128 v[142:145], v142 offset:3072
	ds_read_b128 v[146:149], v158
	ds_read_b128 v[150:153], v158 offset:1024
	ds_read_b128 v[154:157], v158 offset:2048
	ds_read_b128 v[158:161], v158 offset:3072
	v_lshl_add_u64 v[194:195], s[44:45], 0, v[186:187]
	s_add_i32 m0, s93, 0xc000
	ds_read_b128 v[162:165], v201
	ds_read_b128 v[166:169], v201 offset:1024
	ds_read_b128 v[170:173], v201 offset:2048
	ds_read_b128 v[174:177], v201 offset:3072
	ds_read_b128 v[190:193], v201 offset:4096
	ds_read_b128 v[202:205], v201 offset:5120
	ds_read_b128 v[206:209], v201 offset:6144
	ds_read_b128 v[210:213], v201 offset:7168
	global_load_lds_dwordx4 v[194:195], off
	v_lshl_add_u64 v[194:195], s[44:45], 0, v[188:189]
	s_add_i32 m0, s93, 0xe000
	s_nop 0
	global_load_lds_dwordx4 v[194:195], off
	s_waitcnt lgkmcnt(0)
	s_setprio 1
	s_barrier
; #define PG8_STAGE(bufoff, gbase, voff) do { _Pragma("unroll") for (int _i = 0; _i < 2; ++_i) \
;         __builtin_amdgcn_global_load_lds((const unsigned*)((const char*)(gbase) + (voff)[_i]), (LAS unsigned*)(lds + (bufoff) + ldsw + _i * 8192), 16, 0, 0); } while (0)
; #define PG8_LDA(dst, b, h) do { _Pragma("unroll") for (int m = 0; m < 4; ++m) _Pragma("unroll") for (int k = 0; k < 2; ++k) dst[m][k] = *(const LAS bf16x8*)(lds + PG8_SA(b, h) + aoff + m * 2048 + k * 1024); } while (0)
; #define PG8_LDB(dst, b, h) do { _Pragma("unroll") for (int n = 0; n < 2; ++n) _Pragma("unroll") for (int k = 0; k < 2; ++k) dst[n][k] = *(const LAS bf16x8*)(lds + PG8_SB(b, h) + boff + n * 2048 + k * 1024); } while (0)
; #define PG8_MMA(ai, bj, At, Bt) do { __builtin_amdgcn_s_setprio(1); _Pragma("unroll") for (int m = 0; m < 4; ++m) _Pragma("unroll") for (int n = 0; n < 2; ++n) _Pragma("unroll") for (int k = 0; k < 2; ++k) \
;         acc[ai][bj][m][n] = __builtin_amdgcn_mfma_f32_16x16x32_bf16(Bt[n][k], At[m][k], acc[ai][bj][m][n], 0, 0, 0); __builtin_amdgcn_s_setprio(0); } while (0)
; #define PG8_WAIT_V(n) asm volatile("s_waitcnt vmcnt(" #n ")" ::: "memory")
; #define PG8_WAIT_L(n) asm volatile("s_waitcnt lgkmcnt(" #n ")" ::: "memory")
; #define PG8_BAR __builtin_amdgcn_s_barrier()
; #define PG8_SCHED __builtin_amdgcn_sched_barrier(0)
; template <class Epi, int AMODE>
; __device__ __forceinline__ void gemm_phase(LAS unsigned char* lds, const Gemm g, const StaticOrder& S, const Epi& E, int stagger_us, int tid_in) {
;     ...
;             PG8_LDB(B0, 0, 0); PG8_LDB(B1, 0, 1); PG8_SCHED; PG8_LDA(At, 0, 0); PG8_STAGE(PG8_SA(1, 1), a1 + hstepA, voffA);
;             PG8_WAIT_V(8); PG8_WAIT_L(0); PG8_BAR; PG8_MMA(0, 0, At, B0); PG8_MMA(0, 1, At, B1); PG8_BAR; PG8_SCHED;
;             PG8_LDA(At, 0, 1); PG8_STAGE(PG8_SB(0, 0), b2, voffB); PG8_STAGE(PG8_SB(0, 1), b2 + hstepB, voffB); PG8_STAGE(PG8_SA(0, 0), a2, voffA);
;             PG8_WAIT_V(8); PG8_WAIT_L(0); PG8_BAR; PG8_MMA(1, 0, At, B0); PG8_MMA(1, 1, At, B1); PG8_BAR; PG8_SCHED;
	v_mfma_f32_16x16x32_bf16 v[126:129], v[130:133], v[162:165], v[126:129]
	v_mfma_f32_16x16x32_bf16 v[122:125], v[138:141], v[162:165], v[122:125]
	v_mfma_f32_16x16x32_bf16 v[118:121], v[130:133], v[170:173], v[118:121]
	v_mfma_f32_16x16x32_bf16 v[114:117], v[138:141], v[170:173], v[114:117]
	v_mfma_f32_16x16x32_bf16 v[110:113], v[130:133], v[190:193], v[110:113]
	v_mfma_f32_16x16x32_bf16 v[102:105], v[138:141], v[190:193], v[102:105]
	v_mfma_f32_16x16x32_bf16 v[90:93], v[130:133], v[206:209], v[90:93]
	v_mfma_f32_16x16x32_bf16 v[82:85], v[138:141], v[206:209], v[82:85]
	v_mfma_f32_16x16x32_bf16 v[126:129], v[134:137], v[166:169], v[126:129]
	v_mfma_f32_16x16x32_bf16 v[122:125], v[142:145], v[166:169], v[122:125]
	v_mfma_f32_16x16x32_bf16 v[118:121], v[134:137], v[174:177], v[118:121]
	v_mfma_f32_16x16x32_bf16 v[114:117], v[142:145], v[174:177], v[114:117]
	v_mfma_f32_16x16x32_bf16 v[110:113], v[134:137], v[202:205], v[110:113]
	v_mfma_f32_16x16x32_bf16 v[102:105], v[142:145], v[202:205], v[102:105]
	v_mfma_f32_16x16x32_bf16 v[90:93], v[134:137], v[210:213], v[90:93]
	v_mfma_f32_16x16x32_bf16 v[82:85], v[142:145], v[210:213], v[82:85]
	v_mfma_f32_16x16x32_bf16 v[106:109], v[146:149], v[162:165], v[106:109]
	v_mfma_f32_16x16x32_bf16 v[98:101], v[154:157], v[162:165], v[98:101]
	v_mfma_f32_16x16x32_bf16 v[94:97], v[146:149], v[170:173], v[94:97]
	v_mfma_f32_16x16x32_bf16 v[86:89], v[154:157], v[170:173], v[86:89]
	v_mfma_f32_16x16x32_bf16 v[70:73], v[146:149], v[190:193], v[70:73]
	v_mfma_f32_16x16x32_bf16 v[62:65], v[154:157], v[190:193], v[62:65]
	v_mfma_f32_16x16x32_bf16 v[78:81], v[146:149], v[206:209], v[78:81]
	v_mfma_f32_16x16x32_bf16 v[66:69], v[154:157], v[206:209], v[66:69]
	v_mfma_f32_16x16x32_bf16 v[106:109], v[150:153], v[166:169], v[106:109]
	v_mfma_f32_16x16x32_bf16 v[98:101], v[158:161], v[166:169], v[98:101]
	v_mfma_f32_16x16x32_bf16 v[94:97], v[150:153], v[174:177], v[94:97]
	v_mfma_f32_16x16x32_bf16 v[86:89], v[158:161], v[174:177], v[86:89]
	v_mfma_f32_16x16x32_bf16 v[70:73], v[150:153], v[202:205], v[70:73]
	v_mfma_f32_16x16x32_bf16 v[62:65], v[158:161], v[202:205], v[62:65]
	v_mfma_f32_16x16x32_bf16 v[78:81], v[150:153], v[210:213], v[78:81]
	v_mfma_f32_16x16x32_bf16 v[66:69], v[158:161], v[210:213], v[66:69]
	s_setprio 0
	s_barrier
	s_add_i32 s34, s34, s91
	v_lshl_add_u64 v[194:195], s[6:7], 0, v[0:1]
	s_mov_b32 m0, s34
	ds_read_b128 v[162:165], v201 offset:16384
	ds_read_b128 v[166:169], v201 offset:17408
	ds_read_b128 v[170:173], v201 offset:18432
	ds_read_b128 v[174:177], v201 offset:19456
	ds_read_b128 v[190:193], v201 offset:20480
	ds_read_b128 v[202:205], v201 offset:21504
	ds_read_b128 v[206:209], v201 offset:22528
	ds_read_b128 v[210:213], v201 offset:23552
	global_load_lds_dwordx4 v[194:195], off
	s_add_i32 m0, s34, 0x2000
	s_add_u32 s44, s6, 0x80000
	v_lshl_add_u64 v[214:215], s[6:7], 0, v[182:183]
	s_addc_u32 s45, s7, 0
	s_add_i32 s34, s35, s91
	global_load_lds_dwordx4 v[214:215], off
	v_lshl_add_u64 v[216:217], s[44:45], 0, v[0:1]
	s_mov_b32 m0, s34
	v_lshl_add_u64 v[218:219], s[42:43], 0, v[180:181]
	global_load_lds_dwordx4 v[216:217], off
	v_lshl_add_u64 v[216:217], s[44:45], 0, v[182:183]
	s_add_i32 m0, s34, 0x2000
	s_nop 0
	global_load_lds_dwordx4 v[216:217], off
	v_lshl_add_u64 v[216:217], s[42:43], 0, v[178:179]
	s_mov_b32 m0, s93
	s_nop 0
	global_load_lds_dwordx4 v[216:217], off
	s_mov_b32 m0, s83
	s_nop 0
	global_load_lds_dwordx4 v[218:219], off
	s_waitcnt lgkmcnt(0)
	s_setprio 1
	s_barrier
	v_mfma_f32_16x16x32_bf16 v[54:57], v[130:133], v[162:165], v[54:57]
	v_mfma_f32_16x16x32_bf16 v[46:49], v[138:141], v[162:165], v[46:49]
	v_mfma_f32_16x16x32_bf16 v[38:41], v[130:133], v[170:173], v[38:41]
	v_mfma_f32_16x16x32_bf16 v[50:53], v[138:141], v[170:173], v[50:53]
	v_mfma_f32_16x16x32_bf16 v[18:21], v[130:133], v[190:193], v[18:21]
	v_mfma_f32_16x16x32_bf16 v[34:37], v[138:141], v[190:193], v[34:37]
	v_mfma_f32_16x16x32_bf16 v[22:25], v[130:133], v[206:209], v[22:25]
	v_mfma_f32_16x16x32_bf16 v[74:77], v[138:141], v[206:209], v[74:77]
	v_mfma_f32_16x16x32_bf16 v[54:57], v[134:137], v[166:169], v[54:57]
	v_mfma_f32_16x16x32_bf16 v[46:49], v[142:145], v[166:169], v[46:49]
	v_mfma_f32_16x16x32_bf16 v[38:41], v[134:137], v[174:177], v[38:41]
	v_mfma_f32_16x16x32_bf16 v[50:53], v[142:145], v[174:177], v[50:53]
	v_mfma_f32_16x16x32_bf16 v[18:21], v[134:137], v[202:205], v[18:21]
	v_mfma_f32_16x16x32_bf16 v[34:37], v[142:145], v[202:205], v[34:37]
	v_mfma_f32_16x16x32_bf16 v[22:25], v[134:137], v[210:213], v[22:25]
	v_mfma_f32_16x16x32_bf16 v[74:77], v[142:145], v[210:213], v[74:77]
	v_mfma_f32_16x16x32_bf16 v[58:61], v[146:149], v[162:165], v[58:61]
	v_mfma_f32_16x16x32_bf16 v[30:33], v[154:157], v[162:165], v[30:33]
	v_mfma_f32_16x16x32_bf16 v[42:45], v[146:149], v[170:173], v[42:45]
	v_mfma_f32_16x16x32_bf16 v[6:9], v[154:157], v[170:173], v[6:9]
	v_mfma_f32_16x16x32_bf16 v[26:29], v[146:149], v[190:193], v[26:29]
	v_mfma_f32_16x16x32_bf16 v[10:13], v[154:157], v[190:193], v[10:13]
	v_mfma_f32_16x16x32_bf16 v[14:17], v[146:149], v[206:209], v[14:17]
	v_mfma_f32_16x16x32_bf16 v[2:5], v[154:157], v[206:209], v[2:5]
	v_mfma_f32_16x16x32_bf16 v[58:61], v[150:153], v[166:169], v[58:61]
	v_mfma_f32_16x16x32_bf16 v[30:33], v[158:161], v[166:169], v[30:33]
	v_mfma_f32_16x16x32_bf16 v[42:45], v[150:153], v[174:177], v[42:45]
	v_mfma_f32_16x16x32_bf16 v[6:9], v[158:161], v[174:177], v[6:9]
	v_mfma_f32_16x16x32_bf16 v[26:29], v[150:153], v[202:205], v[26:29]
	v_mfma_f32_16x16x32_bf16 v[10:13], v[158:161], v[202:205], v[10:13]
	v_mfma_f32_16x16x32_bf16 v[14:17], v[150:153], v[210:213], v[14:17]
	v_mfma_f32_16x16x32_bf16 v[2:5], v[158:161], v[210:213], v[2:5]
	s_setprio 0
	s_barrier
; #define PG8_STAGE(bufoff, gbase, voff) do { _Pragma("unroll") for (int _i = 0; _i < 2; ++_i) \
;         __builtin_amdgcn_global_load_lds((const unsigned*)((const char*)(gbase) + (voff)[_i]), (LAS unsigned*)(lds + (bufoff) + ldsw + _i * 8192), 16, 0, 0); } while (0)
; #define PG8_LDA(dst, b, h) do { _Pragma("unroll") for (int m = 0; m < 4; ++m) _Pragma("unroll") for (int k = 0; k < 2; ++k) dst[m][k] = *(const LAS bf16x8*)(lds + PG8_SA(b, h) + aoff + m * 2048 + k * 1024); } while (0)
; #define PG8_LDB(dst, b, h) do { _Pragma("unroll") for (int n = 0; n < 2; ++n) _Pragma("unroll") for (int k = 0; k < 2; ++k) dst[n][k] = *(const LAS bf16x8*)(lds + PG8_SB(b, h) + boff + n * 2048 + k * 1024); } while (0)
; #define PG8_MMA(ai, bj, At, Bt) do { __builtin_amdgcn_s_setprio(1); _Pragma("unroll") for (int m = 0; m < 4; ++m) _Pragma("unroll") for (int n = 0; n < 2; ++n) _Pragma("unroll") for (int k = 0; k < 2; ++k) \
;         acc[ai][bj][m][n] = __builtin_amdgcn_mfma_f32_16x16x32_bf16(Bt[n][k], At[m][k], acc[ai][bj][m][n], 0, 0, 0); __builtin_amdgcn_s_setprio(0); } while (0)
; #define PG8_WAIT_V(n) asm volatile("s_waitcnt vmcnt(" #n ")" ::: "memory")
; #define PG8_WAIT_L(n) asm volatile("s_waitcnt lgkmcnt(" #n ")" ::: "memory")
; #define PG8_BAR __builtin_amdgcn_s_barrier()
; #define PG8_SCHED __builtin_amdgcn_sched_barrier(0)
; template <class Epi, int AMODE>
; __device__ __forceinline__ void gemm_phase(LAS unsigned char* lds, const Gemm g, const StaticOrder& S, const Epi& E, int stagger_us, int tid_in) {
;     ...
;             PG8_LDB(B0, 1, 0); PG8_LDB(B1, 1, 1); PG8_SCHED; PG8_LDA(At, 1, 0); PG8_STAGE(PG8_SA(0, 1), a2 + hstepA, voffA);
;             PG8_WAIT_V(8); PG8_WAIT_L(0); PG8_BAR; PG8_MMA(0, 0, At, B0); PG8_MMA(0, 1, At, B1); PG8_BAR; PG8_SCHED;
;             PG8_LDA(At, 1, 1); PG8_STAGE(PG8_SB(1, 0), b3, voffB); PG8_STAGE(PG8_SB(1, 1), b3 + hstepB, voffB); PG8_STAGE(PG8_SA(1, 0), a3, voffA);
;             PG8_WAIT_V(8); PG8_WAIT_L(0); PG8_BAR; PG8_MMA(1, 0, At, B0); PG8_MMA(1, 1, At, B1); PG8_BAR; PG8_SCHED;
	s_add_i32 s34, 0, 0x18000
	s_add_i32 s35, 0, 0x1c000
	v_add_u32_e32 v142, s34, v196
	v_add_u32_e32 v158, s35, v196
	ds_read_b128 v[130:133], v142
	ds_read_b128 v[134:137], v142 offset:1024
	ds_read_b128 v[138:141], v142 offset:2048
	ds_read_b128 v[142:145], v142 offset:3072
	ds_read_b128 v[146:149], v158
	ds_read_b128 v[150:153], v158 offset:1024
	ds_read_b128 v[154:157], v158 offset:2048
	ds_read_b128 v[158:161], v158 offset:3072
	s_add_u32 s42, s42, 0x4000
	s_addc_u32 s43, s43, 0
	s_mov_b32 m0, s79
	v_lshl_add_u64 v[220:221], s[42:43], 0, v[178:179]
	ds_read_b128 v[162:165], v201 offset:32768
	ds_read_b128 v[166:169], v201 offset:33792
	ds_read_b128 v[170:173], v201 offset:34816
	ds_read_b128 v[174:177], v201 offset:35840
	ds_read_b128 v[190:193], v201 offset:36864
	ds_read_b128 v[202:205], v201 offset:37888
	ds_read_b128 v[206:209], v201 offset:38912
	ds_read_b128 v[210:213], v201 offset:39936
	global_load_lds_dwordx4 v[220:221], off
	v_lshl_add_u64 v[220:221], s[42:43], 0, v[180:181]
	s_mov_b32 m0, s87
	s_nop 0
	global_load_lds_dwordx4 v[220:221], off
	s_waitcnt vmcnt(8)
	s_waitcnt lgkmcnt(0)
	s_setprio 1
	s_barrier
	v_mfma_f32_16x16x32_bf16 v[126:129], v[130:133], v[162:165], v[126:129]
	v_mfma_f32_16x16x32_bf16 v[122:125], v[138:141], v[162:165], v[122:125]
	v_mfma_f32_16x16x32_bf16 v[118:121], v[130:133], v[170:173], v[118:121]
	v_mfma_f32_16x16x32_bf16 v[114:117], v[138:141], v[170:173], v[114:117]
	v_mfma_f32_16x16x32_bf16 v[110:113], v[130:133], v[190:193], v[110:113]
	v_mfma_f32_16x16x32_bf16 v[102:105], v[138:141], v[190:193], v[102:105]
	v_mfma_f32_16x16x32_bf16 v[90:93], v[130:133], v[206:209], v[90:93]
	v_mfma_f32_16x16x32_bf16 v[82:85], v[138:141], v[206:209], v[82:85]
	v_mfma_f32_16x16x32_bf16 v[126:129], v[134:137], v[166:169], v[126:129]
	v_mfma_f32_16x16x32_bf16 v[122:125], v[142:145], v[166:169], v[122:125]
	v_mfma_f32_16x16x32_bf16 v[118:121], v[134:137], v[174:177], v[118:121]
	v_mfma_f32_16x16x32_bf16 v[114:117], v[142:145], v[174:177], v[114:117]
	v_mfma_f32_16x16x32_bf16 v[110:113], v[134:137], v[202:205], v[110:113]
	v_mfma_f32_16x16x32_bf16 v[102:105], v[142:145], v[202:205], v[102:105]
	v_mfma_f32_16x16x32_bf16 v[90:93], v[134:137], v[210:213], v[90:93]
	v_mfma_f32_16x16x32_bf16 v[82:85], v[142:145], v[210:213], v[82:85]
	v_mfma_f32_16x16x32_bf16 v[106:109], v[146:149], v[162:165], v[106:109]
	v_mfma_f32_16x16x32_bf16 v[98:101], v[154:157], v[162:165], v[98:101]
	v_mfma_f32_16x16x32_bf16 v[94:97], v[146:149], v[170:173], v[94:97]
	v_mfma_f32_16x16x32_bf16 v[86:89], v[154:157], v[170:173], v[86:89]
	v_mfma_f32_16x16x32_bf16 v[70:73], v[146:149], v[190:193], v[70:73]
	v_mfma_f32_16x16x32_bf16 v[62:65], v[154:157], v[190:193], v[62:65]
	v_mfma_f32_16x16x32_bf16 v[78:81], v[146:149], v[206:209], v[78:81]
	v_mfma_f32_16x16x32_bf16 v[66:69], v[154:157], v[206:209], v[66:69]
	v_mfma_f32_16x16x32_bf16 v[106:109], v[150:153], v[166:169], v[106:109]
	v_mfma_f32_16x16x32_bf16 v[98:101], v[158:161], v[166:169], v[98:101]
	v_mfma_f32_16x16x32_bf16 v[94:97], v[150:153], v[174:177], v[94:97]
	v_mfma_f32_16x16x32_bf16 v[86:89], v[158:161], v[174:177], v[86:89]
	v_mfma_f32_16x16x32_bf16 v[70:73], v[150:153], v[202:205], v[70:73]
	v_mfma_f32_16x16x32_bf16 v[62:65], v[158:161], v[202:205], v[62:65]
	v_mfma_f32_16x16x32_bf16 v[78:81], v[150:153], v[210:213], v[78:81]
	v_mfma_f32_16x16x32_bf16 v[66:69], v[158:161], v[210:213], v[66:69]
	s_setprio 0
	s_barrier
	s_add_i32 s34, s34, s91
	v_lshl_add_u64 v[194:195], v[194:195], 0, s[74:75]
	s_mov_b32 m0, s34
	ds_read_b128 v[162:165], v201 offset:49152
	ds_read_b128 v[166:169], v201 offset:50176
	ds_read_b128 v[170:173], v201 offset:51200
	ds_read_b128 v[174:177], v201 offset:52224
	ds_read_b128 v[190:193], v201 offset:53248
	ds_read_b128 v[202:205], v201 offset:54272
	ds_read_b128 v[206:209], v201 offset:55296
	ds_read_b128 v[210:213], v201 offset:56320
	global_load_lds_dwordx4 v[194:195], off
	s_add_i32 m0, s34, 0x2000
	s_add_u32 s6, s6, 0x80080
	v_lshl_add_u64 v[194:195], v[214:215], 0, s[74:75]
	s_addc_u32 s7, s7, 0
	s_add_i32 s34, s35, s91
	global_load_lds_dwordx4 v[194:195], off
	v_lshl_add_u64 v[194:195], s[6:7], 0, v[0:1]
	s_mov_b32 m0, s34
	s_nop 0
	global_load_lds_dwordx4 v[194:195], off
	v_lshl_add_u64 v[194:195], s[6:7], 0, v[182:183]
	s_add_i32 m0, s34, 0x2000
	s_nop 0
	global_load_lds_dwordx4 v[194:195], off
	v_lshl_add_u64 v[194:195], v[216:217], 0, s[74:75]
	s_mov_b32 m0, s67
	s_nop 0
	global_load_lds_dwordx4 v[194:195], off
	v_lshl_add_u64 v[194:195], v[218:219], 0, s[74:75]
	s_mov_b32 m0, s85
	s_nop 0
	global_load_lds_dwordx4 v[194:195], off
	s_waitcnt vmcnt(8)
	s_waitcnt lgkmcnt(0)
	s_setprio 1
	s_barrier
	v_mfma_f32_16x16x32_bf16 v[54:57], v[130:133], v[162:165], v[54:57]
	v_mfma_f32_16x16x32_bf16 v[46:49], v[138:141], v[162:165], v[46:49]
	v_mfma_f32_16x16x32_bf16 v[38:41], v[130:133], v[170:173], v[38:41]
	v_mfma_f32_16x16x32_bf16 v[50:53], v[138:141], v[170:173], v[50:53]
	v_mfma_f32_16x16x32_bf16 v[18:21], v[130:133], v[190:193], v[18:21]
	v_mfma_f32_16x16x32_bf16 v[34:37], v[138:141], v[190:193], v[34:37]
	v_mfma_f32_16x16x32_bf16 v[22:25], v[130:133], v[206:209], v[22:25]
	v_mfma_f32_16x16x32_bf16 v[74:77], v[138:141], v[206:209], v[74:77]
	v_mfma_f32_16x16x32_bf16 v[54:57], v[134:137], v[166:169], v[54:57]
	v_mfma_f32_16x16x32_bf16 v[46:49], v[142:145], v[166:169], v[46:49]
	v_mfma_f32_16x16x32_bf16 v[38:41], v[134:137], v[174:177], v[38:41]
	v_mfma_f32_16x16x32_bf16 v[50:53], v[142:145], v[174:177], v[50:53]
	v_mfma_f32_16x16x32_bf16 v[18:21], v[134:137], v[202:205], v[18:21]
	v_mfma_f32_16x16x32_bf16 v[34:37], v[142:145], v[202:205], v[34:37]
	v_mfma_f32_16x16x32_bf16 v[22:25], v[134:137], v[210:213], v[22:25]
	v_mfma_f32_16x16x32_bf16 v[74:77], v[142:145], v[210:213], v[74:77]
	v_mfma_f32_16x16x32_bf16 v[58:61], v[146:149], v[162:165], v[58:61]
	v_mfma_f32_16x16x32_bf16 v[30:33], v[154:157], v[162:165], v[30:33]
	v_mfma_f32_16x16x32_bf16 v[42:45], v[146:149], v[170:173], v[42:45]
	v_mfma_f32_16x16x32_bf16 v[6:9], v[154:157], v[170:173], v[6:9]
	v_mfma_f32_16x16x32_bf16 v[26:29], v[146:149], v[190:193], v[26:29]
	v_mfma_f32_16x16x32_bf16 v[10:13], v[154:157], v[190:193], v[10:13]
	v_mfma_f32_16x16x32_bf16 v[14:17], v[146:149], v[206:209], v[14:17]
	v_mfma_f32_16x16x32_bf16 v[2:5], v[154:157], v[206:209], v[2:5]
	v_mfma_f32_16x16x32_bf16 v[58:61], v[150:153], v[166:169], v[58:61]
	v_mfma_f32_16x16x32_bf16 v[30:33], v[158:161], v[166:169], v[30:33]
	v_mfma_f32_16x16x32_bf16 v[42:45], v[150:153], v[174:177], v[42:45]
	v_mfma_f32_16x16x32_bf16 v[6:9], v[158:161], v[174:177], v[6:9]
	v_mfma_f32_16x16x32_bf16 v[26:29], v[150:153], v[202:205], v[26:29]
	v_mfma_f32_16x16x32_bf16 v[10:13], v[158:161], v[202:205], v[10:13]
	v_mfma_f32_16x16x32_bf16 v[14:17], v[150:153], v[210:213], v[14:17]
	v_mfma_f32_16x16x32_bf16 v[2:5], v[158:161], v[210:213], v[2:5]
	s_setprio 0
	s_barrier
	s_add_i32 s31, s31, 2
	s_add_u32 s29, s29, 0x100
	s_addc_u32 s30, s30, 0
	s_cmp_gt_u32 s31, 29
	s_mov_b64 s[44:45], s[4:5]
; #define PG8_STAGE(bufoff, gbase, voff) do { _Pragma("unroll") for (int _i = 0; _i < 2; ++_i) \
;         __builtin_amdgcn_global_load_lds((const unsigned*)((const char*)(gbase) + (voff)[_i]), (LAS unsigned*)(lds + (bufoff) + ldsw + _i * 8192), 16, 0, 0); } while (0)
; #define PG8_LDA(dst, b, h) do { _Pragma("unroll") for (int m = 0; m < 4; ++m) _Pragma("unroll") for (int k = 0; k < 2; ++k) dst[m][k] = *(const LAS bf16x8*)(lds + PG8_SA(b, h) + aoff + m * 2048 + k * 1024); } while (0)
; #define PG8_LDB(dst, b, h) do { _Pragma("unroll") for (int n = 0; n < 2; ++n) _Pragma("unroll") for (int k = 0; k < 2; ++k) dst[n][k] = *(const LAS bf16x8*)(lds + PG8_SB(b, h) + boff + n * 2048 + k * 1024); } while (0)
; #define PG8_MMA(ai, bj, At, Bt) do { __builtin_amdgcn_s_setprio(1); _Pragma("unroll") for (int m = 0; m < 4; ++m) _Pragma("unroll") for (int n = 0; n < 2; ++n) _Pragma("unroll") for (int k = 0; k < 2; ++k) \
;         acc[ai][bj][m][n] = __builtin_amdgcn_mfma_f32_16x16x32_bf16(Bt[n][k], At[m][k], acc[ai][bj][m][n], 0, 0, 0); __builtin_amdgcn_s_setprio(0); } while (0)
; #define PG8_BAR __builtin_amdgcn_s_barrier()
; template <class Epi, int AMODE>
; __device__ __forceinline__ void gemm_phase(LAS unsigned char* lds, const Gemm g, const StaticOrder& S, const Epi& E, int stagger_us, int tid_in) {
;     ...
;         const bool has_next = S.next(ui + 1, nxt);
;         const char* nA = has_next ? Abase + (size_t)nxt.pm * tstepA : cA; const char* nB = has_next ? (const char*)g.Bt + (size_t)nxt.pn * tstepB : cB;
;         for (int t = 0; t < nt; t += 2) {
;             const bool last = (t == nt - 2);
;             const char* a1 = cA + (size_t)(t + 1) * kstep;
;             const char* a2 = last ? nA : cA + (size_t)(t + 2) * kstep; const char* b2 = last ? nB : cB + (size_t)(t + 2) * kstep;
;             const char* a3 = a2 + kstep; const char* b3 = b2 + kstep;
;             PG8_LDB(B0, 0, 0); PG8_LDB(B1, 0, 1); PG8_SCHED; PG8_LDA(At, 0, 0); PG8_STAGE(PG8_SA(1, 1), a1 + hstepA, voffA);
;             PG8_WAIT_V(8); PG8_WAIT_L(0); PG8_BAR; PG8_MMA(0, 0, At, B0); PG8_MMA(0, 1, At, B1); PG8_BAR; PG8_SCHED;
;             PG8_LDA(At, 0, 1); PG8_STAGE(PG8_SB(0, 0), b2, voffB); PG8_STAGE(PG8_SB(0, 1), b2 + hstepB, voffB); PG8_STAGE(PG8_SA(0, 0), a2, voffA);
;             PG8_WAIT_V(8); PG8_WAIT_L(0); PG8_BAR; PG8_MMA(1, 0, At, B0); PG8_MMA(1, 1, At, B1); PG8_BAR; PG8_SCHED;
.LBB0_1299:
	s_add_u32 s4, s44, 0x100
	s_addc_u32 s5, s45, 0
	s_add_i32 s34, 0, 0x10000
	s_cmp_eq_u32 s31, 28
	s_cselect_b32 s43, s95, s5
	s_cselect_b32 s42, s94, s4
	s_cselect_b32 s7, s27, s30
	s_cselect_b32 s6, s28, s29
	s_add_i32 s35, 0, 0x14000
	v_add_u32_e32 v142, s34, v196
	v_add_u32_e32 v158, s35, v196
	ds_read_b128 v[130:133], v142
	ds_read_b128 v[134:137], v142 offset:1024
	ds_read_b128 v[138:141], v142 offset:2048
	ds_read_b128 v[142:145], v142 offset:3072
	ds_read_b128 v[146:149], v158
	ds_read_b128 v[150:153], v158 offset:1024
	ds_read_b128 v[154:157], v158 offset:2048
	ds_read_b128 v[158:161], v158 offset:3072
	v_lshl_add_u64 v[194:195], s[44:45], 0, v[186:187]
	s_add_i32 m0, s93, 0xc000
	ds_read_b128 v[162:165], v201
	ds_read_b128 v[166:169], v201 offset:1024
	ds_read_b128 v[170:173], v201 offset:2048
	ds_read_b128 v[174:177], v201 offset:3072
	ds_read_b128 v[190:193], v201 offset:4096
	ds_read_b128 v[202:205], v201 offset:5120
	ds_read_b128 v[206:209], v201 offset:6144
	ds_read_b128 v[210:213], v201 offset:7168
	global_load_lds_dwordx4 v[194:195], off
	v_lshl_add_u64 v[194:195], s[44:45], 0, v[188:189]
	s_add_i32 m0, s93, 0xe000
	s_nop 0
	global_load_lds_dwordx4 v[194:195], off
	s_waitcnt vmcnt(8)
	s_waitcnt lgkmcnt(0)
	s_setprio 1
	s_barrier
	v_mfma_f32_16x16x32_bf16 v[126:129], v[130:133], v[162:165], v[126:129]
	v_mfma_f32_16x16x32_bf16 v[122:125], v[138:141], v[162:165], v[122:125]
	v_mfma_f32_16x16x32_bf16 v[118:121], v[130:133], v[170:173], v[118:121]
	v_mfma_f32_16x16x32_bf16 v[114:117], v[138:141], v[170:173], v[114:117]
	v_mfma_f32_16x16x32_bf16 v[110:113], v[130:133], v[190:193], v[110:113]
	v_mfma_f32_16x16x32_bf16 v[102:105], v[138:141], v[190:193], v[102:105]
	v_mfma_f32_16x16x32_bf16 v[90:93], v[130:133], v[206:209], v[90:93]
	v_mfma_f32_16x16x32_bf16 v[82:85], v[138:141], v[206:209], v[82:85]
	v_mfma_f32_16x16x32_bf16 v[126:129], v[134:137], v[166:169], v[126:129]
	v_mfma_f32_16x16x32_bf16 v[122:125], v[142:145], v[166:169], v[122:125]
	v_mfma_f32_16x16x32_bf16 v[118:121], v[134:137], v[174:177], v[118:121]
	v_mfma_f32_16x16x32_bf16 v[114:117], v[142:145], v[174:177], v[114:117]
	v_mfma_f32_16x16x32_bf16 v[110:113], v[134:137], v[202:205], v[110:113]
	v_mfma_f32_16x16x32_bf16 v[102:105], v[142:145], v[202:205], v[102:105]
	v_mfma_f32_16x16x32_bf16 v[90:93], v[134:137], v[210:213], v[90:93]
	v_mfma_f32_16x16x32_bf16 v[82:85], v[142:145], v[210:213], v[82:85]
	v_mfma_f32_16x16x32_bf16 v[106:109], v[146:149], v[162:165], v[106:109]
	v_mfma_f32_16x16x32_bf16 v[98:101], v[154:157], v[162:165], v[98:101]
	v_mfma_f32_16x16x32_bf16 v[94:97], v[146:149], v[170:173], v[94:97]
	v_mfma_f32_16x16x32_bf16 v[86:89], v[154:157], v[170:173], v[86:89]
	v_mfma_f32_16x16x32_bf16 v[70:73], v[146:149], v[190:193], v[70:73]
	v_mfma_f32_16x16x32_bf16 v[62:65], v[154:157], v[190:193], v[62:65]
	v_mfma_f32_16x16x32_bf16 v[78:81], v[146:149], v[206:209], v[78:81]
	v_mfma_f32_16x16x32_bf16 v[66:69], v[154:157], v[206:209], v[66:69]
	v_mfma_f32_16x16x32_bf16 v[106:109], v[150:153], v[166:169], v[106:109]
	v_mfma_f32_16x16x32_bf16 v[98:101], v[158:161], v[166:169], v[98:101]
	v_mfma_f32_16x16x32_bf16 v[94:97], v[150:153], v[174:177], v[94:97]
	v_mfma_f32_16x16x32_bf16 v[86:89], v[158:161], v[174:177], v[86:89]
	v_mfma_f32_16x16x32_bf16 v[70:73], v[150:153], v[202:205], v[70:73]
	v_mfma_f32_16x16x32_bf16 v[62:65], v[158:161], v[202:205], v[62:65]
	v_mfma_f32_16x16x32_bf16 v[78:81], v[150:153], v[210:213], v[78:81]
	v_mfma_f32_16x16x32_bf16 v[66:69], v[158:161], v[210:213], v[66:69]
	s_setprio 0
	s_barrier
	s_add_i32 s34, s34, s91
	v_lshl_add_u64 v[194:195], s[6:7], 0, v[0:1]
	s_mov_b32 m0, s34
	ds_read_b128 v[162:165], v201 offset:16384
	ds_read_b128 v[166:169], v201 offset:17408
	ds_read_b128 v[170:173], v201 offset:18432
	ds_read_b128 v[174:177], v201 offset:19456
	ds_read_b128 v[190:193], v201 offset:20480
	ds_read_b128 v[202:205], v201 offset:21504
	ds_read_b128 v[206:209], v201 offset:22528
	ds_read_b128 v[210:213], v201 offset:23552
	global_load_lds_dwordx4 v[194:195], off
	s_add_i32 m0, s34, 0x2000
	s_add_u32 s44, s6, 0x80000
	v_lshl_add_u64 v[214:215], s[6:7], 0, v[182:183]
	s_addc_u32 s45, s7, 0
	s_add_i32 s34, s35, s91
	global_load_lds_dwordx4 v[214:215], off
	v_lshl_add_u64 v[216:217], s[44:45], 0, v[0:1]
	s_mov_b32 m0, s34
	v_lshl_add_u64 v[218:219], s[42:43], 0, v[180:181]
	global_load_lds_dwordx4 v[216:217], off
	v_lshl_add_u64 v[216:217], s[44:45], 0, v[182:183]
	s_add_i32 m0, s34, 0x2000
	s_nop 0
	global_load_lds_dwordx4 v[216:217], off
	v_lshl_add_u64 v[216:217], s[42:43], 0, v[178:179]
	s_mov_b32 m0, s93
	s_nop 0
	global_load_lds_dwordx4 v[216:217], off
	s_mov_b32 m0, s83
	s_nop 0
	global_load_lds_dwordx4 v[218:219], off
	s_waitcnt vmcnt(8)
	s_waitcnt lgkmcnt(0)
	s_setprio 1
	s_barrier
; #define PG8_STAGE(bufoff, gbase, voff) do { _Pragma("unroll") for (int _i = 0; _i < 2; ++_i) \
;         __builtin_amdgcn_global_load_lds((const unsigned*)((const char*)(gbase) + (voff)[_i]), (LAS unsigned*)(lds + (bufoff) + ldsw + _i * 8192), 16, 0, 0); } while (0)
; #define PG8_LDA(dst, b, h) do { _Pragma("unroll") for (int m = 0; m < 4; ++m) _Pragma("unroll") for (int k = 0; k < 2; ++k) dst[m][k] = *(const LAS bf16x8*)(lds + PG8_SA(b, h) + aoff + m * 2048 + k * 1024); } while (0)
; #define PG8_LDB(dst, b, h) do { _Pragma("unroll") for (int n = 0; n < 2; ++n) _Pragma("unroll") for (int k = 0; k < 2; ++k) dst[n][k] = *(const LAS bf16x8*)(lds + PG8_SB(b, h) + boff + n * 2048 + k * 1024); } while (0)
; #define PG8_MMA(ai, bj, At, Bt) do { __builtin_amdgcn_s_setprio(1); _Pragma("unroll") for (int m = 0; m < 4; ++m) _Pragma("unroll") for (int n = 0; n < 2; ++n) _Pragma("unroll") for (int k = 0; k < 2; ++k) \
;         acc[ai][bj][m][n] = __builtin_amdgcn_mfma_f32_16x16x32_bf16(Bt[n][k], At[m][k], acc[ai][bj][m][n], 0, 0, 0); __builtin_amdgcn_s_setprio(0); } while (0)
; #define PG8_WAIT_V(n) asm volatile("s_waitcnt vmcnt(" #n ")" ::: "memory")
; #define PG8_WAIT_L(n) asm volatile("s_waitcnt lgkmcnt(" #n ")" ::: "memory")
; #define PG8_BAR __builtin_amdgcn_s_barrier()
; #define PG8_SCHED __builtin_amdgcn_sched_barrier(0)
; template <class Epi, int AMODE>
; __device__ __forceinline__ void gemm_phase(LAS unsigned char* lds, const Gemm g, const StaticOrder& S, const Epi& E, int stagger_us, int tid_in) {
;     ...
;             PG8_WAIT_V(8); PG8_WAIT_L(0); PG8_BAR; PG8_MMA(1, 0, At, B0); PG8_MMA(1, 1, At, B1); PG8_BAR; PG8_SCHED;
;             PG8_LDB(B0, 1, 0); PG8_LDB(B1, 1, 1); PG8_SCHED; PG8_LDA(At, 1, 0); PG8_STAGE(PG8_SA(0, 1), a2 + hstepA, voffA);
;             PG8_WAIT_V(8); PG8_WAIT_L(0); PG8_BAR; PG8_MMA(0, 0, At, B0); PG8_MMA(0, 1, At, B1); PG8_BAR; PG8_SCHED;
	v_mfma_f32_16x16x32_bf16 v[54:57], v[130:133], v[162:165], v[54:57]
	v_mfma_f32_16x16x32_bf16 v[46:49], v[138:141], v[162:165], v[46:49]
	v_mfma_f32_16x16x32_bf16 v[38:41], v[130:133], v[170:173], v[38:41]
	v_mfma_f32_16x16x32_bf16 v[50:53], v[138:141], v[170:173], v[50:53]
	v_mfma_f32_16x16x32_bf16 v[18:21], v[130:133], v[190:193], v[18:21]
	v_mfma_f32_16x16x32_bf16 v[34:37], v[138:141], v[190:193], v[34:37]
	v_mfma_f32_16x16x32_bf16 v[22:25], v[130:133], v[206:209], v[22:25]
	v_mfma_f32_16x16x32_bf16 v[74:77], v[138:141], v[206:209], v[74:77]
	v_mfma_f32_16x16x32_bf16 v[54:57], v[134:137], v[166:169], v[54:57]
	v_mfma_f32_16x16x32_bf16 v[46:49], v[142:145], v[166:169], v[46:49]
	v_mfma_f32_16x16x32_bf16 v[38:41], v[134:137], v[174:177], v[38:41]
	v_mfma_f32_16x16x32_bf16 v[50:53], v[142:145], v[174:177], v[50:53]
	v_mfma_f32_16x16x32_bf16 v[18:21], v[134:137], v[202:205], v[18:21]
	v_mfma_f32_16x16x32_bf16 v[34:37], v[142:145], v[202:205], v[34:37]
	v_mfma_f32_16x16x32_bf16 v[22:25], v[134:137], v[210:213], v[22:25]
	v_mfma_f32_16x16x32_bf16 v[74:77], v[142:145], v[210:213], v[74:77]
	v_mfma_f32_16x16x32_bf16 v[58:61], v[146:149], v[162:165], v[58:61]
	v_mfma_f32_16x16x32_bf16 v[30:33], v[154:157], v[162:165], v[30:33]
	v_mfma_f32_16x16x32_bf16 v[42:45], v[146:149], v[170:173], v[42:45]
	v_mfma_f32_16x16x32_bf16 v[6:9], v[154:157], v[170:173], v[6:9]
	v_mfma_f32_16x16x32_bf16 v[26:29], v[146:149], v[190:193], v[26:29]
	v_mfma_f32_16x16x32_bf16 v[10:13], v[154:157], v[190:193], v[10:13]
	v_mfma_f32_16x16x32_bf16 v[14:17], v[146:149], v[206:209], v[14:17]
	v_mfma_f32_16x16x32_bf16 v[2:5], v[154:157], v[206:209], v[2:5]
	v_mfma_f32_16x16x32_bf16 v[58:61], v[150:153], v[166:169], v[58:61]
	v_mfma_f32_16x16x32_bf16 v[30:33], v[158:161], v[166:169], v[30:33]
	v_mfma_f32_16x16x32_bf16 v[42:45], v[150:153], v[174:177], v[42:45]
	v_mfma_f32_16x16x32_bf16 v[6:9], v[158:161], v[174:177], v[6:9]
	v_mfma_f32_16x16x32_bf16 v[26:29], v[150:153], v[202:205], v[26:29]
	v_mfma_f32_16x16x32_bf16 v[10:13], v[158:161], v[202:205], v[10:13]
	v_mfma_f32_16x16x32_bf16 v[14:17], v[150:153], v[210:213], v[14:17]
	v_mfma_f32_16x16x32_bf16 v[2:5], v[158:161], v[210:213], v[2:5]
	s_setprio 0
	s_barrier
	s_add_i32 s34, 0, 0x18000
	s_add_i32 s35, 0, 0x1c000
	v_add_u32_e32 v142, s34, v196
	v_add_u32_e32 v158, s35, v196
	ds_read_b128 v[130:133], v142
	ds_read_b128 v[134:137], v142 offset:1024
	ds_read_b128 v[138:141], v142 offset:2048
	ds_read_b128 v[142:145], v142 offset:3072
	ds_read_b128 v[146:149], v158
	ds_read_b128 v[150:153], v158 offset:1024
	ds_read_b128 v[154:157], v158 offset:2048
	ds_read_b128 v[158:161], v158 offset:3072
	s_add_u32 s42, s42, 0x4000
	s_addc_u32 s43, s43, 0
	s_mov_b32 m0, s79
	v_lshl_add_u64 v[220:221], s[42:43], 0, v[178:179]
	ds_read_b128 v[162:165], v201 offset:32768
	ds_read_b128 v[166:169], v201 offset:33792
	ds_read_b128 v[170:173], v201 offset:34816
	ds_read_b128 v[174:177], v201 offset:35840
	ds_read_b128 v[190:193], v201 offset:36864
	ds_read_b128 v[202:205], v201 offset:37888
	ds_read_b128 v[206:209], v201 offset:38912
	ds_read_b128 v[210:213], v201 offset:39936
	global_load_lds_dwordx4 v[220:221], off
	v_lshl_add_u64 v[220:221], s[42:43], 0, v[180:181]
	s_mov_b32 m0, s87
	s_nop 0
	global_load_lds_dwordx4 v[220:221], off
	s_waitcnt vmcnt(8)
	s_waitcnt lgkmcnt(0)
	s_setprio 1
	s_barrier
	v_mfma_f32_16x16x32_bf16 v[126:129], v[130:133], v[162:165], v[126:129]
	v_mfma_f32_16x16x32_bf16 v[122:125], v[138:141], v[162:165], v[122:125]
	v_mfma_f32_16x16x32_bf16 v[118:121], v[130:133], v[170:173], v[118:121]
	v_mfma_f32_16x16x32_bf16 v[114:117], v[138:141], v[170:173], v[114:117]
	v_mfma_f32_16x16x32_bf16 v[110:113], v[130:133], v[190:193], v[110:113]
	v_mfma_f32_16x16x32_bf16 v[102:105], v[138:141], v[190:193], v[102:105]
	v_mfma_f32_16x16x32_bf16 v[90:93], v[130:133], v[206:209], v[90:93]
	v_mfma_f32_16x16x32_bf16 v[82:85], v[138:141], v[206:209], v[82:85]
	v_mfma_f32_16x16x32_bf16 v[126:129], v[134:137], v[166:169], v[126:129]
	v_mfma_f32_16x16x32_bf16 v[122:125], v[142:145], v[166:169], v[122:125]
	v_mfma_f32_16x16x32_bf16 v[118:121], v[134:137], v[174:177], v[118:121]
	v_mfma_f32_16x16x32_bf16 v[114:117], v[142:145], v[174:177], v[114:117]
	v_mfma_f32_16x16x32_bf16 v[110:113], v[134:137], v[202:205], v[110:113]
	v_mfma_f32_16x16x32_bf16 v[102:105], v[142:145], v[202:205], v[102:105]
	v_mfma_f32_16x16x32_bf16 v[90:93], v[134:137], v[210:213], v[90:93]
	v_mfma_f32_16x16x32_bf16 v[82:85], v[142:145], v[210:213], v[82:85]
	v_mfma_f32_16x16x32_bf16 v[106:109], v[146:149], v[162:165], v[106:109]
	v_mfma_f32_16x16x32_bf16 v[98:101], v[154:157], v[162:165], v[98:101]
	v_mfma_f32_16x16x32_bf16 v[94:97], v[146:149], v[170:173], v[94:97]
	v_mfma_f32_16x16x32_bf16 v[86:89], v[154:157], v[170:173], v[86:89]
	v_mfma_f32_16x16x32_bf16 v[70:73], v[146:149], v[190:193], v[70:73]
	v_mfma_f32_16x16x32_bf16 v[62:65], v[154:157], v[190:193], v[62:65]
	v_mfma_f32_16x16x32_bf16 v[78:81], v[146:149], v[206:209], v[78:81]
	v_mfma_f32_16x16x32_bf16 v[66:69], v[154:157], v[206:209], v[66:69]
	v_mfma_f32_16x16x32_bf16 v[106:109], v[150:153], v[166:169], v[106:109]
	v_mfma_f32_16x16x32_bf16 v[98:101], v[158:161], v[166:169], v[98:101]
	v_mfma_f32_16x16x32_bf16 v[94:97], v[150:153], v[174:177], v[94:97]
	v_mfma_f32_16x16x32_bf16 v[86:89], v[158:161], v[174:177], v[86:89]
	v_mfma_f32_16x16x32_bf16 v[70:73], v[150:153], v[202:205], v[70:73]
	v_mfma_f32_16x16x32_bf16 v[62:65], v[158:161], v[202:205], v[62:65]
	v_mfma_f32_16x16x32_bf16 v[78:81], v[150:153], v[210:213], v[78:81]
	v_mfma_f32_16x16x32_bf16 v[66:69], v[158:161], v[210:213], v[66:69]
	s_setprio 0
	s_barrier
; #define PG8_STAGE(bufoff, gbase, voff) do { _Pragma("unroll") for (int _i = 0; _i < 2; ++_i) \
;         __builtin_amdgcn_global_load_lds((const unsigned*)((const char*)(gbase) + (voff)[_i]), (LAS unsigned*)(lds + (bufoff) + ldsw + _i * 8192), 16, 0, 0); } while (0)
; #define PG8_LDA(dst, b, h) do { _Pragma("unroll") for (int m = 0; m < 4; ++m) _Pragma("unroll") for (int k = 0; k < 2; ++k) dst[m][k] = *(const LAS bf16x8*)(lds + PG8_SA(b, h) + aoff + m * 2048 + k * 1024); } while (0)
; #define PG8_MMA(ai, bj, At, Bt) do { __builtin_amdgcn_s_setprio(1); _Pragma("unroll") for (int m = 0; m < 4; ++m) _Pragma("unroll") for (int n = 0; n < 2; ++n) _Pragma("unroll") for (int k = 0; k < 2; ++k) \
;         acc[ai][bj][m][n] = __builtin_amdgcn_mfma_f32_16x16x32_bf16(Bt[n][k], At[m][k], acc[ai][bj][m][n], 0, 0, 0); __builtin_amdgcn_s_setprio(0); } while (0)
; #define PG8_WAIT_V(n) asm volatile("s_waitcnt vmcnt(" #n ")" ::: "memory")
; #define PG8_WAIT_L(n) asm volatile("s_waitcnt lgkmcnt(" #n ")" ::: "memory")
; #define PG8_BAR __builtin_amdgcn_s_barrier()
; #define PG8_SCHED __builtin_amdgcn_sched_barrier(0)
; template <class Epi, int AMODE>
; __device__ __forceinline__ void gemm_phase(LAS unsigned char* lds, const Gemm g, const StaticOrder& S, const Epi& E, int stagger_us, int tid_in) {
;     ...
;             PG8_LDA(At, 1, 1); PG8_STAGE(PG8_SB(1, 0), b3, voffB); PG8_STAGE(PG8_SB(1, 1), b3 + hstepB, voffB); PG8_STAGE(PG8_SA(1, 0), a3, voffA);
;             PG8_WAIT_V(8); PG8_WAIT_L(0); PG8_BAR; PG8_MMA(1, 0, At, B0); PG8_MMA(1, 1, At, B1); PG8_BAR; PG8_SCHED;
;         }
;         if (wr == 0) PG8_BAR;
	s_add_i32 s34, s34, s91
	v_lshl_add_u64 v[194:195], v[194:195], 0, s[74:75]
	s_mov_b32 m0, s34
	ds_read_b128 v[162:165], v201 offset:49152
	ds_read_b128 v[166:169], v201 offset:50176
	ds_read_b128 v[170:173], v201 offset:51200
	ds_read_b128 v[174:177], v201 offset:52224
	ds_read_b128 v[190:193], v201 offset:53248
	ds_read_b128 v[202:205], v201 offset:54272
	ds_read_b128 v[206:209], v201 offset:55296
	ds_read_b128 v[210:213], v201 offset:56320
	global_load_lds_dwordx4 v[194:195], off
	s_add_i32 m0, s34, 0x2000
	s_add_u32 s6, s6, 0x80080
	v_lshl_add_u64 v[194:195], v[214:215], 0, s[74:75]
	s_addc_u32 s7, s7, 0
	s_add_i32 s34, s35, s91
	global_load_lds_dwordx4 v[194:195], off
	v_lshl_add_u64 v[194:195], s[6:7], 0, v[0:1]
	s_mov_b32 m0, s34
	s_nop 0
	global_load_lds_dwordx4 v[194:195], off
	v_lshl_add_u64 v[194:195], s[6:7], 0, v[182:183]
	s_add_i32 m0, s34, 0x2000
	s_nop 0
	global_load_lds_dwordx4 v[194:195], off
	v_lshl_add_u64 v[194:195], v[216:217], 0, s[74:75]
	s_mov_b32 m0, s67
	s_nop 0
	global_load_lds_dwordx4 v[194:195], off
	v_lshl_add_u64 v[194:195], v[218:219], 0, s[74:75]
	s_mov_b32 m0, s85
	s_nop 0
	global_load_lds_dwordx4 v[194:195], off
	s_waitcnt vmcnt(8)
	s_waitcnt lgkmcnt(0)
	s_setprio 1
	s_barrier
	v_mfma_f32_16x16x32_bf16 v[54:57], v[130:133], v[162:165], v[54:57]
	v_mfma_f32_16x16x32_bf16 v[46:49], v[138:141], v[162:165], v[46:49]
	v_mfma_f32_16x16x32_bf16 v[38:41], v[130:133], v[170:173], v[38:41]
	v_mfma_f32_16x16x32_bf16 v[50:53], v[138:141], v[170:173], v[50:53]
	v_mfma_f32_16x16x32_bf16 v[18:21], v[130:133], v[190:193], v[18:21]
	v_mfma_f32_16x16x32_bf16 v[34:37], v[138:141], v[190:193], v[34:37]
	v_mfma_f32_16x16x32_bf16 v[22:25], v[130:133], v[206:209], v[22:25]
	v_mfma_f32_16x16x32_bf16 v[74:77], v[138:141], v[206:209], v[74:77]
	v_mfma_f32_16x16x32_bf16 v[54:57], v[134:137], v[166:169], v[54:57]
	v_mfma_f32_16x16x32_bf16 v[46:49], v[142:145], v[166:169], v[46:49]
	v_mfma_f32_16x16x32_bf16 v[38:41], v[134:137], v[174:177], v[38:41]
	v_mfma_f32_16x16x32_bf16 v[50:53], v[142:145], v[174:177], v[50:53]
	v_mfma_f32_16x16x32_bf16 v[18:21], v[134:137], v[202:205], v[18:21]
	v_mfma_f32_16x16x32_bf16 v[34:37], v[142:145], v[202:205], v[34:37]
	v_mfma_f32_16x16x32_bf16 v[22:25], v[134:137], v[210:213], v[22:25]
	v_mfma_f32_16x16x32_bf16 v[74:77], v[142:145], v[210:213], v[74:77]
	v_mfma_f32_16x16x32_bf16 v[58:61], v[146:149], v[162:165], v[58:61]
	v_mfma_f32_16x16x32_bf16 v[30:33], v[154:157], v[162:165], v[30:33]
	v_mfma_f32_16x16x32_bf16 v[42:45], v[146:149], v[170:173], v[42:45]
	v_mfma_f32_16x16x32_bf16 v[6:9], v[154:157], v[170:173], v[6:9]
	v_mfma_f32_16x16x32_bf16 v[26:29], v[146:149], v[190:193], v[26:29]
	v_mfma_f32_16x16x32_bf16 v[10:13], v[154:157], v[190:193], v[10:13]
	v_mfma_f32_16x16x32_bf16 v[14:17], v[146:149], v[206:209], v[14:17]
	v_mfma_f32_16x16x32_bf16 v[2:5], v[154:157], v[206:209], v[2:5]
	v_mfma_f32_16x16x32_bf16 v[58:61], v[150:153], v[166:169], v[58:61]
	v_mfma_f32_16x16x32_bf16 v[30:33], v[158:161], v[166:169], v[30:33]
	v_mfma_f32_16x16x32_bf16 v[42:45], v[150:153], v[174:177], v[42:45]
	v_mfma_f32_16x16x32_bf16 v[6:9], v[158:161], v[174:177], v[6:9]
	v_mfma_f32_16x16x32_bf16 v[26:29], v[150:153], v[202:205], v[26:29]
	v_mfma_f32_16x16x32_bf16 v[10:13], v[158:161], v[202:205], v[10:13]
	v_mfma_f32_16x16x32_bf16 v[14:17], v[150:153], v[210:213], v[14:17]
	v_mfma_f32_16x16x32_bf16 v[2:5], v[158:161], v[210:213], v[2:5]
	s_setprio 0
	s_barrier
	s_add_i32 s31, s31, 2
	s_add_u32 s29, s29, 0x100
	s_addc_u32 s30, s30, 0
	s_cmp_gt_u32 s31, 29
	s_mov_b64 s[44:45], s[4:5]
	s_cbranch_scc0 .LBB0_1299
	s_and_b64 vcc, exec, s[48:49]
	s_cbranch_vccz .LBB0_1302
	s_barrier

; #define PG8_STAGE(bufoff, gbase, voff) do { _Pragma("unroll") for (int _i = 0; _i < 2; ++_i) \
;         __builtin_amdgcn_global_load_lds((const unsigned*)((const char*)(gbase) + (voff)[_i]), (LAS unsigned*)(lds + (bufoff) + ldsw + _i * 8192), 16, 0, 0); } while (0)
; #define PG8_LDA(dst, b, h) do { _Pragma("unroll") for (int m = 0; m < 4; ++m) _Pragma("unroll") for (int k = 0; k < 2; ++k) dst[m][k] = *(const LAS bf16x8*)(lds + PG8_SA(b, h) + aoff + m * 2048 + k * 1024); } while (0)
; #define PG8_LDB(dst, b, h) do { _Pragma("unroll") for (int n = 0; n < 2; ++n) _Pragma("unroll") for (int k = 0; k < 2; ++k) dst[n][k] = *(const LAS bf16x8*)(lds + PG8_SB(b, h) + boff + n * 2048 + k * 1024); } while (0)
; #define PG8_MMA(ai, bj, At, Bt) do { __builtin_amdgcn_s_setprio(1); _Pragma("unroll") for (int m = 0; m < 4; ++m) _Pragma("unroll") for (int n = 0; n < 2; ++n) _Pragma("unroll") for (int k = 0; k < 2; ++k) \
;         acc[ai][bj][m][n] = __builtin_amdgcn_mfma_f32_16x16x32_bf16(Bt[n][k], At[m][k], acc[ai][bj][m][n], 0, 0, 0); __builtin_amdgcn_s_setprio(0); } while (0)
; #define PG8_BAR __builtin_amdgcn_s_barrier()
; template <class Epi, int AMODE>
; __device__ __forceinline__ void gemm_phase(LAS unsigned char* lds, const Gemm g, const StaticOrder& S, const Epi& E, int stagger_us, int tid_in) {
;     ...
;         const bool has_next = S.next(ui + 1, nxt);
;         const char* nA = has_next ? Abase + (size_t)nxt.pm * tstepA : cA; const char* nB = has_next ? (const char*)g.Bt + (size_t)nxt.pn * tstepB : cB;
;         for (int t = 0; t < nt; t += 2) {
;             const bool last = (t == nt - 2);
;             const char* a1 = cA + (size_t)(t + 1) * kstep;
;             const char* a2 = last ? nA : cA + (size_t)(t + 2) * kstep; const char* b2 = last ? nB : cB + (size_t)(t + 2) * kstep;
;             const char* a3 = a2 + kstep; const char* b3 = b2 + kstep;
;             PG8_LDB(B0, 0, 0); PG8_LDB(B1, 0, 1); PG8_SCHED; PG8_LDA(At, 0, 0); PG8_STAGE(PG8_SA(1, 1), a1 + hstepA, voffA);
;             PG8_WAIT_V(8); PG8_WAIT_L(0); PG8_BAR; PG8_MMA(0, 0, At, B0); PG8_MMA(0, 1, At, B1); PG8_BAR; PG8_SCHED;
;             PG8_LDA(At, 0, 1); PG8_STAGE(PG8_SB(0, 0), b2, voffB); PG8_STAGE(PG8_SB(0, 1), b2 + hstepB, voffB); PG8_STAGE(PG8_SA(0, 0), a2, voffA);
;             PG8_WAIT_V(8); PG8_WAIT_L(0); PG8_BAR; PG8_MMA(1, 0, At, B0); PG8_MMA(1, 1, At, B1); PG8_BAR; PG8_SCHED;
.LBB0_1476:
	s_add_u32 s4, s54, 0x100
	s_addc_u32 s5, s55, 0
	s_add_i32 s30, 0, 0x10000
	s_cmpk_eq_i32 s29, 0x52
	s_cselect_b32 s57, s41, s5
	s_cselect_b32 s56, s40, s4
	s_cselect_b32 s7, s53, s28
	s_cselect_b32 s6, s52, s27
	s_add_i32 s34, 0, 0x14000
	v_add_u32_e32 v102, s30, v162
	v_add_u32_e32 v165, s34, v162
	ds_read_b128 v[66:69], v102
	ds_read_b128 v[70:73], v102 offset:1024
	ds_read_b128 v[74:77], v102 offset:2048
	ds_read_b128 v[102:105], v102 offset:3072
	ds_read_b128 v[152:155], v165
	ds_read_b128 v[156:159], v165 offset:1024
	ds_read_b128 v[166:169], v165 offset:2048
	ds_read_b128 v[170:173], v165 offset:3072
	v_lshl_add_u64 v[206:207], s[54:55], 0, v[148:149]
	s_add_i32 m0, s13, 0xc000
	ds_read_b128 v[174:177], v164
	ds_read_b128 v[178:181], v164 offset:1024
	ds_read_b128 v[182:185], v164 offset:2048
	ds_read_b128 v[186:189], v164 offset:3072
	ds_read_b128 v[190:193], v164 offset:4096
	ds_read_b128 v[194:197], v164 offset:5120
	ds_read_b128 v[198:201], v164 offset:6144
	ds_read_b128 v[202:205], v164 offset:7168
	global_load_lds_dwordx4 v[206:207], off
	v_lshl_add_u64 v[206:207], s[54:55], 0, v[150:151]
	s_add_i32 m0, s13, 0xe000
	s_nop 0
	global_load_lds_dwordx4 v[206:207], off
	s_waitcnt vmcnt(8)
	s_waitcnt lgkmcnt(0)
	s_setprio 1
	s_barrier
	v_mfma_f32_16x16x32_bf16 v[142:145], v[66:69], v[174:177], v[142:145]
	v_mfma_f32_16x16x32_bf16 v[138:141], v[74:77], v[174:177], v[138:141]
	v_mfma_f32_16x16x32_bf16 v[134:137], v[66:69], v[182:185], v[134:137]
	v_mfma_f32_16x16x32_bf16 v[130:133], v[74:77], v[182:185], v[130:133]
	v_mfma_f32_16x16x32_bf16 v[110:113], v[66:69], v[190:193], v[110:113]
	v_mfma_f32_16x16x32_bf16 v[106:109], v[74:77], v[190:193], v[106:109]
	v_mfma_f32_16x16x32_bf16 v[98:101], v[66:69], v[198:201], v[98:101]
	v_mfma_f32_16x16x32_bf16 v[94:97], v[74:77], v[198:201], v[94:97]
	v_mfma_f32_16x16x32_bf16 v[142:145], v[70:73], v[178:181], v[142:145]
	v_mfma_f32_16x16x32_bf16 v[138:141], v[102:105], v[178:181], v[138:141]
	v_mfma_f32_16x16x32_bf16 v[134:137], v[70:73], v[186:189], v[134:137]
	v_mfma_f32_16x16x32_bf16 v[130:133], v[102:105], v[186:189], v[130:133]
	v_mfma_f32_16x16x32_bf16 v[110:113], v[70:73], v[194:197], v[110:113]
	v_mfma_f32_16x16x32_bf16 v[106:109], v[102:105], v[194:197], v[106:109]
	v_mfma_f32_16x16x32_bf16 v[98:101], v[70:73], v[202:205], v[98:101]
	v_mfma_f32_16x16x32_bf16 v[94:97], v[102:105], v[202:205], v[94:97]
	v_mfma_f32_16x16x32_bf16 v[126:129], v[152:155], v[174:177], v[126:129]
	v_mfma_f32_16x16x32_bf16 v[122:125], v[166:169], v[174:177], v[122:125]
	v_mfma_f32_16x16x32_bf16 v[118:121], v[152:155], v[182:185], v[118:121]
	v_mfma_f32_16x16x32_bf16 v[114:117], v[166:169], v[182:185], v[114:117]
	v_mfma_f32_16x16x32_bf16 v[90:93], v[152:155], v[190:193], v[90:93]
	v_mfma_f32_16x16x32_bf16 v[86:89], v[166:169], v[190:193], v[86:89]
	v_mfma_f32_16x16x32_bf16 v[82:85], v[152:155], v[198:201], v[82:85]
	v_mfma_f32_16x16x32_bf16 v[78:81], v[166:169], v[198:201], v[78:81]
	v_mfma_f32_16x16x32_bf16 v[126:129], v[156:159], v[178:181], v[126:129]
	v_mfma_f32_16x16x32_bf16 v[122:125], v[170:173], v[178:181], v[122:125]
	v_mfma_f32_16x16x32_bf16 v[118:121], v[156:159], v[186:189], v[118:121]
	v_mfma_f32_16x16x32_bf16 v[114:117], v[170:173], v[186:189], v[114:117]
	v_mfma_f32_16x16x32_bf16 v[90:93], v[156:159], v[194:197], v[90:93]
	v_mfma_f32_16x16x32_bf16 v[86:89], v[170:173], v[194:197], v[86:89]
	v_mfma_f32_16x16x32_bf16 v[82:85], v[156:159], v[202:205], v[82:85]
	v_mfma_f32_16x16x32_bf16 v[78:81], v[170:173], v[202:205], v[78:81]
	s_setprio 0
	s_barrier
	s_add_i32 s30, s30, s12
	v_lshl_add_u64 v[206:207], s[6:7], 0, v[0:1]
	s_mov_b32 m0, s30
	ds_read_b128 v[174:177], v164 offset:16384
	ds_read_b128 v[178:181], v164 offset:17408
	ds_read_b128 v[182:185], v164 offset:18432
	ds_read_b128 v[186:189], v164 offset:19456
	ds_read_b128 v[190:193], v164 offset:20480
	ds_read_b128 v[194:197], v164 offset:21504
	ds_read_b128 v[198:201], v164 offset:22528
	ds_read_b128 v[202:205], v164 offset:23552
	global_load_lds_dwordx4 v[206:207], off
	s_add_i32 m0, s30, 0x2000
	s_add_u32 s30, s6, 0x158000
	v_lshl_add_u64 v[208:209], s[6:7], 0, v[146:147]
	s_addc_u32 s31, s7, 0
	s_add_i32 s34, s34, s12
	global_load_lds_dwordx4 v[208:209], off
	v_lshl_add_u64 v[210:211], s[30:31], 0, v[0:1]
	s_mov_b32 m0, s34
	v_lshl_add_u64 v[212:213], s[56:57], 0, v[146:147]
	global_load_lds_dwordx4 v[210:211], off
	v_lshl_add_u64 v[210:211], s[30:31], 0, v[146:147]
	s_add_i32 m0, s34, 0x2000
	s_nop 0
	global_load_lds_dwordx4 v[210:211], off
	v_lshl_add_u64 v[210:211], s[56:57], 0, v[0:1]
	s_mov_b32 m0, s13
	s_nop 0
	global_load_lds_dwordx4 v[210:211], off
	s_mov_b32 m0, s24
	s_nop 0
	global_load_lds_dwordx4 v[212:213], off
	s_waitcnt vmcnt(8)
	s_waitcnt lgkmcnt(0)
	s_setprio 1
	s_barrier
; #define PG8_STAGE(bufoff, gbase, voff) do { _Pragma("unroll") for (int _i = 0; _i < 2; ++_i) \
;         __builtin_amdgcn_global_load_lds((const unsigned*)((const char*)(gbase) + (voff)[_i]), (LAS unsigned*)(lds + (bufoff) + ldsw + _i * 8192), 16, 0, 0); } while (0)
; #define PG8_LDA(dst, b, h) do { _Pragma("unroll") for (int m = 0; m < 4; ++m) _Pragma("unroll") for (int k = 0; k < 2; ++k) dst[m][k] = *(const LAS bf16x8*)(lds + PG8_SA(b, h) + aoff + m * 2048 + k * 1024); } while (0)
; #define PG8_LDB(dst, b, h) do { _Pragma("unroll") for (int n = 0; n < 2; ++n) _Pragma("unroll") for (int k = 0; k < 2; ++k) dst[n][k] = *(const LAS bf16x8*)(lds + PG8_SB(b, h) + boff + n * 2048 + k * 1024); } while (0)
; #define PG8_MMA(ai, bj, At, Bt) do { __builtin_amdgcn_s_setprio(1); _Pragma("unroll") for (int m = 0; m < 4; ++m) _Pragma("unroll") for (int n = 0; n < 2; ++n) _Pragma("unroll") for (int k = 0; k < 2; ++k) \
;         acc[ai][bj][m][n] = __builtin_amdgcn_mfma_f32_16x16x32_bf16(Bt[n][k], At[m][k], acc[ai][bj][m][n], 0, 0, 0); __builtin_amdgcn_s_setprio(0); } while (0)
; #define PG8_WAIT_V(n) asm volatile("s_waitcnt vmcnt(" #n ")" ::: "memory")
; #define PG8_WAIT_L(n) asm volatile("s_waitcnt lgkmcnt(" #n ")" ::: "memory")
; #define PG8_BAR __builtin_amdgcn_s_barrier()
; #define PG8_SCHED __builtin_amdgcn_sched_barrier(0)
; template <class Epi, int AMODE>
; __device__ __forceinline__ void gemm_phase(LAS unsigned char* lds, const Gemm g, const StaticOrder& S, const Epi& E, int stagger_us, int tid_in) {
;     ...
;             PG8_WAIT_V(8); PG8_WAIT_L(0); PG8_BAR; PG8_MMA(1, 0, At, B0); PG8_MMA(1, 1, At, B1); PG8_BAR; PG8_SCHED;
;             PG8_LDB(B0, 1, 0); PG8_LDB(B1, 1, 1); PG8_SCHED; PG8_LDA(At, 1, 0); PG8_STAGE(PG8_SA(0, 1), a2 + hstepA, voffA);
;             PG8_WAIT_V(8); PG8_WAIT_L(0); PG8_BAR; PG8_MMA(0, 0, At, B0); PG8_MMA(0, 1, At, B1); PG8_BAR; PG8_SCHED;
	v_mfma_f32_16x16x32_bf16 v[62:65], v[66:69], v[174:177], v[62:65]
	v_mfma_f32_16x16x32_bf16 v[58:61], v[74:77], v[174:177], v[58:61]
	v_mfma_f32_16x16x32_bf16 v[54:57], v[66:69], v[182:185], v[54:57]
	v_mfma_f32_16x16x32_bf16 v[50:53], v[74:77], v[182:185], v[50:53]
	v_mfma_f32_16x16x32_bf16 v[30:33], v[66:69], v[190:193], v[30:33]
	v_mfma_f32_16x16x32_bf16 v[26:29], v[74:77], v[190:193], v[26:29]
	v_mfma_f32_16x16x32_bf16 v[22:25], v[66:69], v[198:201], v[22:25]
	v_mfma_f32_16x16x32_bf16 v[10:13], v[74:77], v[198:201], v[10:13]
	v_mfma_f32_16x16x32_bf16 v[62:65], v[70:73], v[178:181], v[62:65]
	v_mfma_f32_16x16x32_bf16 v[58:61], v[102:105], v[178:181], v[58:61]
	v_mfma_f32_16x16x32_bf16 v[54:57], v[70:73], v[186:189], v[54:57]
	v_mfma_f32_16x16x32_bf16 v[50:53], v[102:105], v[186:189], v[50:53]
	v_mfma_f32_16x16x32_bf16 v[30:33], v[70:73], v[194:197], v[30:33]
	v_mfma_f32_16x16x32_bf16 v[26:29], v[102:105], v[194:197], v[26:29]
	v_mfma_f32_16x16x32_bf16 v[22:25], v[70:73], v[202:205], v[22:25]
	v_mfma_f32_16x16x32_bf16 v[10:13], v[102:105], v[202:205], v[10:13]
	v_mfma_f32_16x16x32_bf16 v[46:49], v[152:155], v[174:177], v[46:49]
	v_mfma_f32_16x16x32_bf16 v[42:45], v[166:169], v[174:177], v[42:45]
	v_mfma_f32_16x16x32_bf16 v[38:41], v[152:155], v[182:185], v[38:41]
	v_mfma_f32_16x16x32_bf16 v[34:37], v[166:169], v[182:185], v[34:37]
	v_mfma_f32_16x16x32_bf16 v[18:21], v[152:155], v[190:193], v[18:21]
	v_mfma_f32_16x16x32_bf16 v[14:17], v[166:169], v[190:193], v[14:17]
	v_mfma_f32_16x16x32_bf16 v[6:9], v[152:155], v[198:201], v[6:9]
	v_mfma_f32_16x16x32_bf16 v[2:5], v[166:169], v[198:201], v[2:5]
	v_mfma_f32_16x16x32_bf16 v[46:49], v[156:159], v[178:181], v[46:49]
	v_mfma_f32_16x16x32_bf16 v[42:45], v[170:173], v[178:181], v[42:45]
	v_mfma_f32_16x16x32_bf16 v[38:41], v[156:159], v[186:189], v[38:41]
	v_mfma_f32_16x16x32_bf16 v[34:37], v[170:173], v[186:189], v[34:37]
	v_mfma_f32_16x16x32_bf16 v[18:21], v[156:159], v[194:197], v[18:21]
	v_mfma_f32_16x16x32_bf16 v[14:17], v[170:173], v[194:197], v[14:17]
	v_mfma_f32_16x16x32_bf16 v[6:9], v[156:159], v[202:205], v[6:9]
	v_mfma_f32_16x16x32_bf16 v[2:5], v[170:173], v[202:205], v[2:5]
	s_setprio 0
	s_barrier
	s_add_i32 s34, 0, 0x18000
	s_add_i32 s35, 0, 0x1c000
	v_add_u32_e32 v102, s34, v162
	v_add_u32_e32 v165, s35, v162
	ds_read_b128 v[66:69], v102
	ds_read_b128 v[70:73], v102 offset:1024
	ds_read_b128 v[74:77], v102 offset:2048
	ds_read_b128 v[102:105], v102 offset:3072
	ds_read_b128 v[152:155], v165
	ds_read_b128 v[156:159], v165 offset:1024
	ds_read_b128 v[166:169], v165 offset:2048
	ds_read_b128 v[170:173], v165 offset:3072
	s_add_u32 s30, s56, 0x158000
	s_addc_u32 s31, s57, 0
	s_mov_b32 m0, s25
	v_lshl_add_u64 v[214:215], s[30:31], 0, v[0:1]
	ds_read_b128 v[174:177], v164 offset:32768
	ds_read_b128 v[178:181], v164 offset:33792
	ds_read_b128 v[182:185], v164 offset:34816
	ds_read_b128 v[186:189], v164 offset:35840
	ds_read_b128 v[190:193], v164 offset:36864
	ds_read_b128 v[194:197], v164 offset:37888
	ds_read_b128 v[198:201], v164 offset:38912
	ds_read_b128 v[202:205], v164 offset:39936
	global_load_lds_dwordx4 v[214:215], off
	v_lshl_add_u64 v[214:215], s[30:31], 0, v[146:147]
	s_mov_b32 m0, s66
	s_nop 0
	global_load_lds_dwordx4 v[214:215], off
	s_waitcnt vmcnt(8)
	s_waitcnt lgkmcnt(0)
	s_setprio 1
	s_barrier
	v_mfma_f32_16x16x32_bf16 v[142:145], v[66:69], v[174:177], v[142:145]
	v_mfma_f32_16x16x32_bf16 v[138:141], v[74:77], v[174:177], v[138:141]
	v_mfma_f32_16x16x32_bf16 v[134:137], v[66:69], v[182:185], v[134:137]
	v_mfma_f32_16x16x32_bf16 v[130:133], v[74:77], v[182:185], v[130:133]
	v_mfma_f32_16x16x32_bf16 v[110:113], v[66:69], v[190:193], v[110:113]
	v_mfma_f32_16x16x32_bf16 v[106:109], v[74:77], v[190:193], v[106:109]
	v_mfma_f32_16x16x32_bf16 v[98:101], v[66:69], v[198:201], v[98:101]
	v_mfma_f32_16x16x32_bf16 v[94:97], v[74:77], v[198:201], v[94:97]
	v_mfma_f32_16x16x32_bf16 v[142:145], v[70:73], v[178:181], v[142:145]
	v_mfma_f32_16x16x32_bf16 v[138:141], v[102:105], v[178:181], v[138:141]
	v_mfma_f32_16x16x32_bf16 v[134:137], v[70:73], v[186:189], v[134:137]
	v_mfma_f32_16x16x32_bf16 v[130:133], v[102:105], v[186:189], v[130:133]
	v_mfma_f32_16x16x32_bf16 v[110:113], v[70:73], v[194:197], v[110:113]
	v_mfma_f32_16x16x32_bf16 v[106:109], v[102:105], v[194:197], v[106:109]
	v_mfma_f32_16x16x32_bf16 v[98:101], v[70:73], v[202:205], v[98:101]
	v_mfma_f32_16x16x32_bf16 v[94:97], v[102:105], v[202:205], v[94:97]
	v_mfma_f32_16x16x32_bf16 v[126:129], v[152:155], v[174:177], v[126:129]
	v_mfma_f32_16x16x32_bf16 v[122:125], v[166:169], v[174:177], v[122:125]
	v_mfma_f32_16x16x32_bf16 v[118:121], v[152:155], v[182:185], v[118:121]
	v_mfma_f32_16x16x32_bf16 v[114:117], v[166:169], v[182:185], v[114:117]
	v_mfma_f32_16x16x32_bf16 v[90:93], v[152:155], v[190:193], v[90:93]
	v_mfma_f32_16x16x32_bf16 v[86:89], v[166:169], v[190:193], v[86:89]
	v_mfma_f32_16x16x32_bf16 v[82:85], v[152:155], v[198:201], v[82:85]
	v_mfma_f32_16x16x32_bf16 v[78:81], v[166:169], v[198:201], v[78:81]
	v_mfma_f32_16x16x32_bf16 v[126:129], v[156:159], v[178:181], v[126:129]
	v_mfma_f32_16x16x32_bf16 v[122:125], v[170:173], v[178:181], v[122:125]
	v_mfma_f32_16x16x32_bf16 v[118:121], v[156:159], v[186:189], v[118:121]
	v_mfma_f32_16x16x32_bf16 v[114:117], v[170:173], v[186:189], v[114:117]
	v_mfma_f32_16x16x32_bf16 v[90:93], v[156:159], v[194:197], v[90:93]
	v_mfma_f32_16x16x32_bf16 v[86:89], v[170:173], v[194:197], v[86:89]
	v_mfma_f32_16x16x32_bf16 v[82:85], v[156:159], v[202:205], v[82:85]
	v_mfma_f32_16x16x32_bf16 v[78:81], v[170:173], v[202:205], v[78:81]
	s_setprio 0
	s_barrier
; #define PG8_STAGE(bufoff, gbase, voff) do { _Pragma("unroll") for (int _i = 0; _i < 2; ++_i) \
;         __builtin_amdgcn_global_load_lds((const unsigned*)((const char*)(gbase) + (voff)[_i]), (LAS unsigned*)(lds + (bufoff) + ldsw + _i * 8192), 16, 0, 0); } while (0)
; #define PG8_LDA(dst, b, h) do { _Pragma("unroll") for (int m = 0; m < 4; ++m) _Pragma("unroll") for (int k = 0; k < 2; ++k) dst[m][k] = *(const LAS bf16x8*)(lds + PG8_SA(b, h) + aoff + m * 2048 + k * 1024); } while (0)
; #define PG8_MMA(ai, bj, At, Bt) do { __builtin_amdgcn_s_setprio(1); _Pragma("unroll") for (int m = 0; m < 4; ++m) _Pragma("unroll") for (int n = 0; n < 2; ++n) _Pragma("unroll") for (int k = 0; k < 2; ++k) \
;         acc[ai][bj][m][n] = __builtin_amdgcn_mfma_f32_16x16x32_bf16(Bt[n][k], At[m][k], acc[ai][bj][m][n], 0, 0, 0); __builtin_amdgcn_s_setprio(0); } while (0)
; #define PG8_WAIT_V(n) asm volatile("s_waitcnt vmcnt(" #n ")" ::: "memory")
; #define PG8_WAIT_L(n) asm volatile("s_waitcnt lgkmcnt(" #n ")" ::: "memory")
; #define PG8_BAR __builtin_amdgcn_s_barrier()
; #define PG8_SCHED __builtin_amdgcn_sched_barrier(0)
; template <class Epi, int AMODE>
; __device__ __forceinline__ void gemm_phase(LAS unsigned char* lds, const Gemm g, const StaticOrder& S, const Epi& E, int stagger_us, int tid_in) {
;     ...
;             PG8_LDA(At, 1, 1); PG8_STAGE(PG8_SB(1, 0), b3, voffB); PG8_STAGE(PG8_SB(1, 1), b3 + hstepB, voffB); PG8_STAGE(PG8_SA(1, 0), a3, voffA);
;             PG8_WAIT_V(8); PG8_WAIT_L(0); PG8_BAR; PG8_MMA(1, 0, At, B0); PG8_MMA(1, 1, At, B1); PG8_BAR; PG8_SCHED;
;         }
;         if (wr == 0) PG8_BAR;
	s_add_i32 s30, s34, s12
	v_lshl_add_u64 v[206:207], v[206:207], 0, s[74:75]
	s_mov_b32 m0, s30
	ds_read_b128 v[174:177], v164 offset:49152
	ds_read_b128 v[178:181], v164 offset:50176
	ds_read_b128 v[182:185], v164 offset:51200
	ds_read_b128 v[186:189], v164 offset:52224
	ds_read_b128 v[190:193], v164 offset:53248
	ds_read_b128 v[194:197], v164 offset:54272
	ds_read_b128 v[198:201], v164 offset:55296
	ds_read_b128 v[202:205], v164 offset:56320
	global_load_lds_dwordx4 v[206:207], off
	s_add_i32 m0, s30, 0x2000
	s_add_u32 s6, s6, 0x158080
	v_lshl_add_u64 v[206:207], v[208:209], 0, s[74:75]
	s_addc_u32 s7, s7, 0
	s_add_i32 s30, s35, s12
	global_load_lds_dwordx4 v[206:207], off
	v_lshl_add_u64 v[206:207], s[6:7], 0, v[0:1]
	s_mov_b32 m0, s30
	s_nop 0
	global_load_lds_dwordx4 v[206:207], off
	v_lshl_add_u64 v[206:207], s[6:7], 0, v[146:147]
	s_add_i32 m0, s30, 0x2000
	s_nop 0
	global_load_lds_dwordx4 v[206:207], off
	v_lshl_add_u64 v[206:207], v[210:211], 0, s[74:75]
	s_mov_b32 m0, s67
	s_nop 0
	global_load_lds_dwordx4 v[206:207], off
	v_lshl_add_u64 v[206:207], v[212:213], 0, s[74:75]
	s_mov_b32 m0, s69
	s_nop 0
	global_load_lds_dwordx4 v[206:207], off
	s_waitcnt vmcnt(8)
	s_waitcnt lgkmcnt(0)
	s_setprio 1
	s_barrier
	v_mfma_f32_16x16x32_bf16 v[62:65], v[66:69], v[174:177], v[62:65]
	v_mfma_f32_16x16x32_bf16 v[58:61], v[74:77], v[174:177], v[58:61]
	v_mfma_f32_16x16x32_bf16 v[54:57], v[66:69], v[182:185], v[54:57]
	v_mfma_f32_16x16x32_bf16 v[50:53], v[74:77], v[182:185], v[50:53]
	v_mfma_f32_16x16x32_bf16 v[30:33], v[66:69], v[190:193], v[30:33]
	v_mfma_f32_16x16x32_bf16 v[26:29], v[74:77], v[190:193], v[26:29]
	v_mfma_f32_16x16x32_bf16 v[22:25], v[66:69], v[198:201], v[22:25]
	v_mfma_f32_16x16x32_bf16 v[10:13], v[74:77], v[198:201], v[10:13]
	v_mfma_f32_16x16x32_bf16 v[62:65], v[70:73], v[178:181], v[62:65]
	v_mfma_f32_16x16x32_bf16 v[58:61], v[102:105], v[178:181], v[58:61]
	v_mfma_f32_16x16x32_bf16 v[54:57], v[70:73], v[186:189], v[54:57]
	v_mfma_f32_16x16x32_bf16 v[50:53], v[102:105], v[186:189], v[50:53]
	v_mfma_f32_16x16x32_bf16 v[30:33], v[70:73], v[194:197], v[30:33]
	v_mfma_f32_16x16x32_bf16 v[26:29], v[102:105], v[194:197], v[26:29]
	v_mfma_f32_16x16x32_bf16 v[22:25], v[70:73], v[202:205], v[22:25]
	v_mfma_f32_16x16x32_bf16 v[10:13], v[102:105], v[202:205], v[10:13]
	v_mfma_f32_16x16x32_bf16 v[46:49], v[152:155], v[174:177], v[46:49]
	v_mfma_f32_16x16x32_bf16 v[42:45], v[166:169], v[174:177], v[42:45]
	v_mfma_f32_16x16x32_bf16 v[38:41], v[152:155], v[182:185], v[38:41]
	v_mfma_f32_16x16x32_bf16 v[34:37], v[166:169], v[182:185], v[34:37]
	v_mfma_f32_16x16x32_bf16 v[18:21], v[152:155], v[190:193], v[18:21]
	v_mfma_f32_16x16x32_bf16 v[14:17], v[166:169], v[190:193], v[14:17]
	v_mfma_f32_16x16x32_bf16 v[6:9], v[152:155], v[198:201], v[6:9]
	v_mfma_f32_16x16x32_bf16 v[2:5], v[166:169], v[198:201], v[2:5]
	v_mfma_f32_16x16x32_bf16 v[46:49], v[156:159], v[178:181], v[46:49]
	v_mfma_f32_16x16x32_bf16 v[42:45], v[170:173], v[178:181], v[42:45]
	v_mfma_f32_16x16x32_bf16 v[38:41], v[156:159], v[186:189], v[38:41]
	v_mfma_f32_16x16x32_bf16 v[34:37], v[170:173], v[186:189], v[34:37]
	v_mfma_f32_16x16x32_bf16 v[18:21], v[156:159], v[194:197], v[18:21]
	v_mfma_f32_16x16x32_bf16 v[14:17], v[170:173], v[194:197], v[14:17]
	v_mfma_f32_16x16x32_bf16 v[6:9], v[156:159], v[202:205], v[6:9]
	v_mfma_f32_16x16x32_bf16 v[2:5], v[170:173], v[202:205], v[2:5]
	s_setprio 0
	s_barrier
	s_add_i32 s29, s29, 2
	s_add_u32 s27, s27, 0x100
	s_addc_u32 s28, s28, 0
	s_cmpk_gt_u32 s29, 0x53
	s_mov_b64 s[54:55], s[4:5]
	s_cbranch_scc0 .LBB0_1476
	s_and_b64 vcc, exec, s[46:47]
	s_cbranch_vccz .LBB0_1479
	s_barrier

; #define PG8_STAGE(bufoff, gbase, voff) do { _Pragma("unroll") for (int _i = 0; _i < 2; ++_i) \
;         __builtin_amdgcn_global_load_lds((const unsigned*)((const char*)(gbase) + (voff)[_i]), (LAS unsigned*)(lds + (bufoff) + ldsw + _i * 8192), 16, 0, 0); } while (0)
; #define PG8_LDA(dst, b, h) do { _Pragma("unroll") for (int m = 0; m < 4; ++m) _Pragma("unroll") for (int k = 0; k < 2; ++k) dst[m][k] = *(const LAS bf16x8*)(lds + PG8_SA(b, h) + aoff + m * 2048 + k * 1024); } while (0)
; #define PG8_LDB(dst, b, h) do { _Pragma("unroll") for (int n = 0; n < 2; ++n) _Pragma("unroll") for (int k = 0; k < 2; ++k) dst[n][k] = *(const LAS bf16x8*)(lds + PG8_SB(b, h) + boff + n * 2048 + k * 1024); } while (0)
; #define PG8_MMA(ai, bj, At, Bt) do { __builtin_amdgcn_s_setprio(1); _Pragma("unroll") for (int m = 0; m < 4; ++m) _Pragma("unroll") for (int n = 0; n < 2; ++n) _Pragma("unroll") for (int k = 0; k < 2; ++k) \
;         acc[ai][bj][m][n] = __builtin_amdgcn_mfma_f32_16x16x32_bf16(Bt[n][k], At[m][k], acc[ai][bj][m][n], 0, 0, 0); __builtin_amdgcn_s_setprio(0); } while (0)
; #define PG8_BAR __builtin_amdgcn_s_barrier()
; template <class Epi, int AMODE>
; __device__ __forceinline__ void gemm_phase(LAS unsigned char* lds, const Gemm g, const StaticOrder& S, const Epi& E, int stagger_us, int tid_in) {
;     ...
;         const bool has_next = S.next(ui + 1, nxt);
;         const char* nA = has_next ? Abase + (size_t)nxt.pm * tstepA : cA; const char* nB = has_next ? (const char*)g.Bt + (size_t)nxt.pn * tstepB : cB;
;         for (int t = 0; t < nt; t += 2) {
;             const bool last = (t == nt - 2);
;             const char* a1 = cA + (size_t)(t + 1) * kstep;
;             const char* a2 = last ? nA : cA + (size_t)(t + 2) * kstep; const char* b2 = last ? nB : cB + (size_t)(t + 2) * kstep;
;             const char* a3 = a2 + kstep; const char* b3 = b2 + kstep;
;             PG8_LDB(B0, 0, 0); PG8_LDB(B1, 0, 1); PG8_SCHED; PG8_LDA(At, 0, 0); PG8_STAGE(PG8_SA(1, 1), a1 + hstepA, voffA);
;             PG8_WAIT_V(8); PG8_WAIT_L(0); PG8_BAR; PG8_MMA(0, 0, At, B0); PG8_MMA(0, 1, At, B1); PG8_BAR; PG8_SCHED;
;             PG8_LDA(At, 0, 1); PG8_STAGE(PG8_SB(0, 0), b2, voffB); PG8_STAGE(PG8_SB(0, 1), b2 + hstepB, voffB); PG8_STAGE(PG8_SA(0, 0), a2, voffA);
;             PG8_WAIT_V(8); PG8_WAIT_L(0); PG8_BAR; PG8_MMA(1, 0, At, B0); PG8_MMA(1, 1, At, B1); PG8_BAR; PG8_SCHED;
.LBB0_1498:
	s_add_u32 s4, s46, 0x100
	s_addc_u32 s5, s47, 0
	s_add_i32 s30, 0, 0x10000
	s_cmpk_eq_i32 s29, 0x52
	s_cselect_b32 s59, s41, s5
	s_cselect_b32 s58, s40, s4
	s_cselect_b32 s7, s57, s28
	s_cselect_b32 s6, s56, s27
	s_add_i32 s34, 0, 0x14000
	v_add_u32_e32 v62, s30, v209
	v_add_u32_e32 v158, s34, v209
	ds_read_b128 v[50:53], v62
	ds_read_b128 v[54:57], v62 offset:1024
	ds_read_b128 v[58:61], v62 offset:2048
	ds_read_b128 v[62:65], v62 offset:3072
	ds_read_b128 v[146:149], v158
	ds_read_b128 v[150:153], v158 offset:1024
	ds_read_b128 v[154:157], v158 offset:2048
	ds_read_b128 v[158:161], v158 offset:3072
	v_lshl_add_u64 v[200:201], s[46:47], 0, v[176:177]
	s_add_i32 m0, s13, 0xc000
	ds_read_b128 v[162:165], v215
	ds_read_b128 v[166:169], v215 offset:1024
	ds_read_b128 v[170:173], v215 offset:2048
	ds_read_b128 v[180:183], v215 offset:3072
	ds_read_b128 v[184:187], v215 offset:4096
	ds_read_b128 v[188:191], v215 offset:5120
	ds_read_b128 v[192:195], v215 offset:6144
	ds_read_b128 v[196:199], v215 offset:7168
	global_load_lds_dwordx4 v[200:201], off
	v_lshl_add_u64 v[200:201], s[46:47], 0, v[178:179]
	s_add_i32 m0, s13, 0xe000
	s_nop 0
	global_load_lds_dwordx4 v[200:201], off
	s_waitcnt vmcnt(8)
	s_waitcnt lgkmcnt(0)
	s_setprio 1
	s_barrier
	v_mfma_f32_16x16x32_bf16 v[142:145], v[50:53], v[162:165], v[142:145]
	v_mfma_f32_16x16x32_bf16 v[138:141], v[58:61], v[162:165], v[138:141]
	v_mfma_f32_16x16x32_bf16 v[126:129], v[50:53], v[170:173], v[126:129]
	v_mfma_f32_16x16x32_bf16 v[122:125], v[58:61], v[170:173], v[122:125]
	v_mfma_f32_16x16x32_bf16 v[110:113], v[50:53], v[184:187], v[110:113]
	v_mfma_f32_16x16x32_bf16 v[106:109], v[58:61], v[184:187], v[106:109]
	v_mfma_f32_16x16x32_bf16 v[94:97], v[50:53], v[192:195], v[94:97]
	v_mfma_f32_16x16x32_bf16 v[90:93], v[58:61], v[192:195], v[90:93]
	v_mfma_f32_16x16x32_bf16 v[142:145], v[54:57], v[166:169], v[142:145]
	v_mfma_f32_16x16x32_bf16 v[138:141], v[62:65], v[166:169], v[138:141]
	v_mfma_f32_16x16x32_bf16 v[126:129], v[54:57], v[180:183], v[126:129]
	v_mfma_f32_16x16x32_bf16 v[122:125], v[62:65], v[180:183], v[122:125]
	v_mfma_f32_16x16x32_bf16 v[110:113], v[54:57], v[188:191], v[110:113]
	v_mfma_f32_16x16x32_bf16 v[106:109], v[62:65], v[188:191], v[106:109]
	v_mfma_f32_16x16x32_bf16 v[94:97], v[54:57], v[196:199], v[94:97]
	v_mfma_f32_16x16x32_bf16 v[90:93], v[62:65], v[196:199], v[90:93]
	v_mfma_f32_16x16x32_bf16 v[134:137], v[146:149], v[162:165], v[134:137]
	v_mfma_f32_16x16x32_bf16 v[130:133], v[154:157], v[162:165], v[130:133]
	v_mfma_f32_16x16x32_bf16 v[118:121], v[146:149], v[170:173], v[118:121]
	v_mfma_f32_16x16x32_bf16 v[114:117], v[154:157], v[170:173], v[114:117]
	v_mfma_f32_16x16x32_bf16 v[102:105], v[146:149], v[184:187], v[102:105]
	v_mfma_f32_16x16x32_bf16 v[98:101], v[154:157], v[184:187], v[98:101]
	v_mfma_f32_16x16x32_bf16 v[86:89], v[146:149], v[192:195], v[86:89]
	v_mfma_f32_16x16x32_bf16 v[82:85], v[154:157], v[192:195], v[82:85]
	v_mfma_f32_16x16x32_bf16 v[134:137], v[150:153], v[166:169], v[134:137]
	v_mfma_f32_16x16x32_bf16 v[130:133], v[158:161], v[166:169], v[130:133]
	v_mfma_f32_16x16x32_bf16 v[118:121], v[150:153], v[180:183], v[118:121]
	v_mfma_f32_16x16x32_bf16 v[114:117], v[158:161], v[180:183], v[114:117]
	v_mfma_f32_16x16x32_bf16 v[102:105], v[150:153], v[188:191], v[102:105]
	v_mfma_f32_16x16x32_bf16 v[98:101], v[158:161], v[188:191], v[98:101]
	v_mfma_f32_16x16x32_bf16 v[86:89], v[150:153], v[196:199], v[86:89]
	v_mfma_f32_16x16x32_bf16 v[82:85], v[158:161], v[196:199], v[82:85]
	s_setprio 0
	s_barrier
	s_add_i32 s30, s30, s12
	v_lshl_add_u64 v[200:201], s[6:7], 0, v[0:1]
	s_mov_b32 m0, s30
	ds_read_b128 v[162:165], v215 offset:16384
	ds_read_b128 v[166:169], v215 offset:17408
	ds_read_b128 v[170:173], v215 offset:18432
	ds_read_b128 v[180:183], v215 offset:19456
	ds_read_b128 v[184:187], v215 offset:20480
	ds_read_b128 v[188:191], v215 offset:21504
	ds_read_b128 v[192:195], v215 offset:22528
	ds_read_b128 v[196:199], v215 offset:23552
	global_load_lds_dwordx4 v[200:201], off
	s_add_i32 m0, s30, 0x2000
	s_add_u32 s30, s6, 0x158000
	v_lshl_add_u64 v[202:203], s[6:7], 0, v[174:175]
	s_addc_u32 s31, s7, 0
	s_add_i32 s34, s34, s12
	global_load_lds_dwordx4 v[202:203], off
	v_lshl_add_u64 v[204:205], s[30:31], 0, v[0:1]
	s_mov_b32 m0, s34
	v_lshl_add_u64 v[206:207], s[58:59], 0, v[174:175]
	global_load_lds_dwordx4 v[204:205], off
	v_lshl_add_u64 v[204:205], s[30:31], 0, v[174:175]
	s_add_i32 m0, s34, 0x2000
	s_nop 0
	global_load_lds_dwordx4 v[204:205], off
	v_lshl_add_u64 v[204:205], s[58:59], 0, v[0:1]
	s_mov_b32 m0, s13
	s_nop 0
	global_load_lds_dwordx4 v[204:205], off
	s_mov_b32 m0, s24
	s_nop 0
	global_load_lds_dwordx4 v[206:207], off
	s_waitcnt vmcnt(8)
	s_waitcnt lgkmcnt(0)
	s_setprio 1
	s_barrier
; #define PG8_STAGE(bufoff, gbase, voff) do { _Pragma("unroll") for (int _i = 0; _i < 2; ++_i) \
;         __builtin_amdgcn_global_load_lds((const unsigned*)((const char*)(gbase) + (voff)[_i]), (LAS unsigned*)(lds + (bufoff) + ldsw + _i * 8192), 16, 0, 0); } while (0)
; #define PG8_LDA(dst, b, h) do { _Pragma("unroll") for (int m = 0; m < 4; ++m) _Pragma("unroll") for (int k = 0; k < 2; ++k) dst[m][k] = *(const LAS bf16x8*)(lds + PG8_SA(b, h) + aoff + m * 2048 + k * 1024); } while (0)
; #define PG8_LDB(dst, b, h) do { _Pragma("unroll") for (int n = 0; n < 2; ++n) _Pragma("unroll") for (int k = 0; k < 2; ++k) dst[n][k] = *(const LAS bf16x8*)(lds + PG8_SB(b, h) + boff + n * 2048 + k * 1024); } while (0)
; #define PG8_MMA(ai, bj, At, Bt) do { __builtin_amdgcn_s_setprio(1); _Pragma("unroll") for (int m = 0; m < 4; ++m) _Pragma("unroll") for (int n = 0; n < 2; ++n) _Pragma("unroll") for (int k = 0; k < 2; ++k) \
;         acc[ai][bj][m][n] = __builtin_amdgcn_mfma_f32_16x16x32_bf16(Bt[n][k], At[m][k], acc[ai][bj][m][n], 0, 0, 0); __builtin_amdgcn_s_setprio(0); } while (0)
; #define PG8_WAIT_V(n) asm volatile("s_waitcnt vmcnt(" #n ")" ::: "memory")
; #define PG8_WAIT_L(n) asm volatile("s_waitcnt lgkmcnt(" #n ")" ::: "memory")
; #define PG8_BAR __builtin_amdgcn_s_barrier()
; #define PG8_SCHED __builtin_amdgcn_sched_barrier(0)
; template <class Epi, int AMODE>
; __device__ __forceinline__ void gemm_phase(LAS unsigned char* lds, const Gemm g, const StaticOrder& S, const Epi& E, int stagger_us, int tid_in) {
;     ...
;             PG8_WAIT_V(8); PG8_WAIT_L(0); PG8_BAR; PG8_MMA(1, 0, At, B0); PG8_MMA(1, 1, At, B1); PG8_BAR; PG8_SCHED;
;             PG8_LDB(B0, 1, 0); PG8_LDB(B1, 1, 1); PG8_SCHED; PG8_LDA(At, 1, 0); PG8_STAGE(PG8_SA(0, 1), a2 + hstepA, voffA);
;             PG8_WAIT_V(8); PG8_WAIT_L(0); PG8_BAR; PG8_MMA(0, 0, At, B0); PG8_MMA(0, 1, At, B1); PG8_BAR; PG8_SCHED;
	v_mfma_f32_16x16x32_bf16 v[78:81], v[50:53], v[162:165], v[78:81]
	v_mfma_f32_16x16x32_bf16 v[74:77], v[58:61], v[162:165], v[74:77]
	v_mfma_f32_16x16x32_bf16 v[46:49], v[50:53], v[170:173], v[46:49]
	v_mfma_f32_16x16x32_bf16 v[42:45], v[58:61], v[170:173], v[42:45]
	v_mfma_f32_16x16x32_bf16 v[30:33], v[50:53], v[184:187], v[30:33]
	v_mfma_f32_16x16x32_bf16 v[26:29], v[58:61], v[184:187], v[26:29]
	v_mfma_f32_16x16x32_bf16 v[14:17], v[50:53], v[192:195], v[14:17]
	v_mfma_f32_16x16x32_bf16 v[10:13], v[58:61], v[192:195], v[10:13]
	v_mfma_f32_16x16x32_bf16 v[78:81], v[54:57], v[166:169], v[78:81]
	v_mfma_f32_16x16x32_bf16 v[74:77], v[62:65], v[166:169], v[74:77]
	v_mfma_f32_16x16x32_bf16 v[46:49], v[54:57], v[180:183], v[46:49]
	v_mfma_f32_16x16x32_bf16 v[42:45], v[62:65], v[180:183], v[42:45]
	v_mfma_f32_16x16x32_bf16 v[30:33], v[54:57], v[188:191], v[30:33]
	v_mfma_f32_16x16x32_bf16 v[26:29], v[62:65], v[188:191], v[26:29]
	v_mfma_f32_16x16x32_bf16 v[14:17], v[54:57], v[196:199], v[14:17]
	v_mfma_f32_16x16x32_bf16 v[10:13], v[62:65], v[196:199], v[10:13]
	v_mfma_f32_16x16x32_bf16 v[38:41], v[146:149], v[170:173], v[38:41]
	v_mfma_f32_16x16x32_bf16 v[34:37], v[154:157], v[170:173], v[34:37]
	v_mfma_f32_16x16x32_bf16 v[22:25], v[146:149], v[184:187], v[22:25]
	v_mfma_f32_16x16x32_bf16 v[18:21], v[154:157], v[184:187], v[18:21]
	v_mfma_f32_16x16x32_bf16 v[6:9], v[146:149], v[192:195], v[6:9]
	v_mfma_f32_16x16x32_bf16 v[2:5], v[154:157], v[192:195], v[2:5]
	v_mfma_f32_16x16x32_bf16 v[50:53], v[146:149], v[162:165], v[70:73]
	v_mfma_f32_16x16x32_bf16 v[54:57], v[154:157], v[162:165], v[66:69]
	v_mfma_f32_16x16x32_bf16 v[38:41], v[150:153], v[180:183], v[38:41]
	v_mfma_f32_16x16x32_bf16 v[34:37], v[158:161], v[180:183], v[34:37]
	v_mfma_f32_16x16x32_bf16 v[22:25], v[150:153], v[188:191], v[22:25]
	v_mfma_f32_16x16x32_bf16 v[18:21], v[158:161], v[188:191], v[18:21]
	v_mfma_f32_16x16x32_bf16 v[6:9], v[150:153], v[196:199], v[6:9]
	v_mfma_f32_16x16x32_bf16 v[2:5], v[158:161], v[196:199], v[2:5]
	v_mfma_f32_16x16x32_bf16 v[50:53], v[150:153], v[166:169], v[50:53]
	v_mfma_f32_16x16x32_bf16 v[54:57], v[158:161], v[166:169], v[54:57]
	s_setprio 0
	s_barrier
	s_add_i32 s34, 0, 0x18000
	s_add_i32 s35, 0, 0x1c000
	v_add_u32_e32 v70, s34, v209
	v_add_u32_e32 v158, s35, v209
	ds_read_b128 v[58:61], v70
	ds_read_b128 v[62:65], v70 offset:1024
	ds_read_b128 v[66:69], v70 offset:2048
	ds_read_b128 v[70:73], v70 offset:3072
	ds_read_b128 v[146:149], v158
	ds_read_b128 v[150:153], v158 offset:1024
	ds_read_b128 v[154:157], v158 offset:2048
	ds_read_b128 v[158:161], v158 offset:3072
	s_add_u32 s30, s58, 0x158000
	s_addc_u32 s31, s59, 0
	s_mov_b32 m0, s25
	v_lshl_add_u64 v[210:211], s[30:31], 0, v[0:1]
	ds_read_b128 v[162:165], v215 offset:32768
	ds_read_b128 v[166:169], v215 offset:33792
	ds_read_b128 v[170:173], v215 offset:34816
	ds_read_b128 v[180:183], v215 offset:35840
	ds_read_b128 v[184:187], v215 offset:36864
	ds_read_b128 v[188:191], v215 offset:37888
	ds_read_b128 v[192:195], v215 offset:38912
	ds_read_b128 v[196:199], v215 offset:39936
	global_load_lds_dwordx4 v[210:211], off
	v_lshl_add_u64 v[210:211], s[30:31], 0, v[174:175]
	s_mov_b32 m0, s66
	s_nop 0
	global_load_lds_dwordx4 v[210:211], off
	s_waitcnt vmcnt(8)
	s_waitcnt lgkmcnt(0)
	s_setprio 1
	s_barrier
	v_mfma_f32_16x16x32_bf16 v[142:145], v[58:61], v[162:165], v[142:145]
	v_mfma_f32_16x16x32_bf16 v[138:141], v[66:69], v[162:165], v[138:141]
	v_mfma_f32_16x16x32_bf16 v[126:129], v[58:61], v[170:173], v[126:129]
	v_mfma_f32_16x16x32_bf16 v[122:125], v[66:69], v[170:173], v[122:125]
	v_mfma_f32_16x16x32_bf16 v[110:113], v[58:61], v[184:187], v[110:113]
	v_mfma_f32_16x16x32_bf16 v[106:109], v[66:69], v[184:187], v[106:109]
	v_mfma_f32_16x16x32_bf16 v[94:97], v[58:61], v[192:195], v[94:97]
	v_mfma_f32_16x16x32_bf16 v[90:93], v[66:69], v[192:195], v[90:93]
	v_mfma_f32_16x16x32_bf16 v[142:145], v[62:65], v[166:169], v[142:145]
	v_mfma_f32_16x16x32_bf16 v[138:141], v[70:73], v[166:169], v[138:141]
	v_mfma_f32_16x16x32_bf16 v[126:129], v[62:65], v[180:183], v[126:129]
	v_mfma_f32_16x16x32_bf16 v[122:125], v[70:73], v[180:183], v[122:125]
	v_mfma_f32_16x16x32_bf16 v[110:113], v[62:65], v[188:191], v[110:113]
	v_mfma_f32_16x16x32_bf16 v[106:109], v[70:73], v[188:191], v[106:109]
	v_mfma_f32_16x16x32_bf16 v[94:97], v[62:65], v[196:199], v[94:97]
	v_mfma_f32_16x16x32_bf16 v[90:93], v[70:73], v[196:199], v[90:93]
	v_mfma_f32_16x16x32_bf16 v[134:137], v[146:149], v[162:165], v[134:137]
	v_mfma_f32_16x16x32_bf16 v[130:133], v[154:157], v[162:165], v[130:133]
	v_mfma_f32_16x16x32_bf16 v[118:121], v[146:149], v[170:173], v[118:121]
	v_mfma_f32_16x16x32_bf16 v[114:117], v[154:157], v[170:173], v[114:117]
	v_mfma_f32_16x16x32_bf16 v[102:105], v[146:149], v[184:187], v[102:105]
	v_mfma_f32_16x16x32_bf16 v[98:101], v[154:157], v[184:187], v[98:101]
	v_mfma_f32_16x16x32_bf16 v[86:89], v[146:149], v[192:195], v[86:89]
	v_mfma_f32_16x16x32_bf16 v[82:85], v[154:157], v[192:195], v[82:85]
	v_mfma_f32_16x16x32_bf16 v[134:137], v[150:153], v[166:169], v[134:137]
	v_mfma_f32_16x16x32_bf16 v[130:133], v[158:161], v[166:169], v[130:133]
	v_mfma_f32_16x16x32_bf16 v[118:121], v[150:153], v[180:183], v[118:121]
	v_mfma_f32_16x16x32_bf16 v[114:117], v[158:161], v[180:183], v[114:117]
	v_mfma_f32_16x16x32_bf16 v[102:105], v[150:153], v[188:191], v[102:105]
	v_mfma_f32_16x16x32_bf16 v[98:101], v[158:161], v[188:191], v[98:101]
	v_mfma_f32_16x16x32_bf16 v[86:89], v[150:153], v[196:199], v[86:89]
	v_mfma_f32_16x16x32_bf16 v[82:85], v[158:161], v[196:199], v[82:85]
	s_setprio 0
	s_barrier
; #define PG8_STAGE(bufoff, gbase, voff) do { _Pragma("unroll") for (int _i = 0; _i < 2; ++_i) \
;         __builtin_amdgcn_global_load_lds((const unsigned*)((const char*)(gbase) + (voff)[_i]), (LAS unsigned*)(lds + (bufoff) + ldsw + _i * 8192), 16, 0, 0); } while (0)
; #define PG8_LDA(dst, b, h) do { _Pragma("unroll") for (int m = 0; m < 4; ++m) _Pragma("unroll") for (int k = 0; k < 2; ++k) dst[m][k] = *(const LAS bf16x8*)(lds + PG8_SA(b, h) + aoff + m * 2048 + k * 1024); } while (0)
; #define PG8_MMA(ai, bj, At, Bt) do { __builtin_amdgcn_s_setprio(1); _Pragma("unroll") for (int m = 0; m < 4; ++m) _Pragma("unroll") for (int n = 0; n < 2; ++n) _Pragma("unroll") for (int k = 0; k < 2; ++k) \
;         acc[ai][bj][m][n] = __builtin_amdgcn_mfma_f32_16x16x32_bf16(Bt[n][k], At[m][k], acc[ai][bj][m][n], 0, 0, 0); __builtin_amdgcn_s_setprio(0); } while (0)
; #define PG8_WAIT_V(n) asm volatile("s_waitcnt vmcnt(" #n ")" ::: "memory")
; #define PG8_WAIT_L(n) asm volatile("s_waitcnt lgkmcnt(" #n ")" ::: "memory")
; #define PG8_BAR __builtin_amdgcn_s_barrier()
; #define PG8_SCHED __builtin_amdgcn_sched_barrier(0)
; template <class Epi, int AMODE>
; __device__ __forceinline__ void gemm_phase(LAS unsigned char* lds, const Gemm g, const StaticOrder& S, const Epi& E, int stagger_us, int tid_in) {
;     ...
;             PG8_LDA(At, 1, 1); PG8_STAGE(PG8_SB(1, 0), b3, voffB); PG8_STAGE(PG8_SB(1, 1), b3 + hstepB, voffB); PG8_STAGE(PG8_SA(1, 0), a3, voffA);
;             PG8_WAIT_V(8); PG8_WAIT_L(0); PG8_BAR; PG8_MMA(1, 0, At, B0); PG8_MMA(1, 1, At, B1); PG8_BAR; PG8_SCHED;
;         }
;         if (wr == 0) PG8_BAR;
	s_add_i32 s30, s34, s12
	v_lshl_add_u64 v[200:201], v[200:201], 0, s[74:75]
	s_mov_b32 m0, s30
	ds_read_b128 v[162:165], v215 offset:49152
	ds_read_b128 v[166:169], v215 offset:50176
	ds_read_b128 v[170:173], v215 offset:51200
	ds_read_b128 v[180:183], v215 offset:52224
	ds_read_b128 v[184:187], v215 offset:53248
	ds_read_b128 v[188:191], v215 offset:54272
	ds_read_b128 v[192:195], v215 offset:55296
	ds_read_b128 v[196:199], v215 offset:56320
	global_load_lds_dwordx4 v[200:201], off
	s_add_i32 m0, s30, 0x2000
	s_add_u32 s6, s6, 0x158080
	v_lshl_add_u64 v[200:201], v[202:203], 0, s[74:75]
	s_addc_u32 s7, s7, 0
	s_add_i32 s30, s35, s12
	global_load_lds_dwordx4 v[200:201], off
	v_lshl_add_u64 v[200:201], s[6:7], 0, v[0:1]
	s_mov_b32 m0, s30
	s_nop 0
	global_load_lds_dwordx4 v[200:201], off
	v_lshl_add_u64 v[200:201], s[6:7], 0, v[174:175]
	s_add_i32 m0, s30, 0x2000
	s_nop 0
	global_load_lds_dwordx4 v[200:201], off
	v_lshl_add_u64 v[200:201], v[204:205], 0, s[74:75]
	s_mov_b32 m0, s79
	s_nop 0
	global_load_lds_dwordx4 v[200:201], off
	v_lshl_add_u64 v[200:201], v[206:207], 0, s[74:75]
	s_mov_b32 m0, s83
	s_nop 0
	global_load_lds_dwordx4 v[200:201], off
	s_waitcnt vmcnt(8)
	s_waitcnt lgkmcnt(0)
	s_setprio 1
	s_barrier
	v_mfma_f32_16x16x32_bf16 v[78:81], v[58:61], v[162:165], v[78:81]
	v_mfma_f32_16x16x32_bf16 v[74:77], v[66:69], v[162:165], v[74:77]
	v_mfma_f32_16x16x32_bf16 v[46:49], v[58:61], v[170:173], v[46:49]
	v_mfma_f32_16x16x32_bf16 v[42:45], v[66:69], v[170:173], v[42:45]
	v_mfma_f32_16x16x32_bf16 v[30:33], v[58:61], v[184:187], v[30:33]
	v_mfma_f32_16x16x32_bf16 v[26:29], v[66:69], v[184:187], v[26:29]
	v_mfma_f32_16x16x32_bf16 v[14:17], v[58:61], v[192:195], v[14:17]
	v_mfma_f32_16x16x32_bf16 v[10:13], v[66:69], v[192:195], v[10:13]
	v_mfma_f32_16x16x32_bf16 v[78:81], v[62:65], v[166:169], v[78:81]
	v_mfma_f32_16x16x32_bf16 v[74:77], v[70:73], v[166:169], v[74:77]
	v_mfma_f32_16x16x32_bf16 v[46:49], v[62:65], v[180:183], v[46:49]
	v_mfma_f32_16x16x32_bf16 v[42:45], v[70:73], v[180:183], v[42:45]
	v_mfma_f32_16x16x32_bf16 v[30:33], v[62:65], v[188:191], v[30:33]
	v_mfma_f32_16x16x32_bf16 v[26:29], v[70:73], v[188:191], v[26:29]
	v_mfma_f32_16x16x32_bf16 v[14:17], v[62:65], v[196:199], v[14:17]
	v_mfma_f32_16x16x32_bf16 v[10:13], v[70:73], v[196:199], v[10:13]
	v_mfma_f32_16x16x32_bf16 v[50:53], v[146:149], v[162:165], v[50:53]
	v_mfma_f32_16x16x32_bf16 v[70:73], v[150:153], v[166:169], v[50:53]
	v_mfma_f32_16x16x32_bf16 v[50:53], v[154:157], v[162:165], v[54:57]
	v_mfma_f32_16x16x32_bf16 v[38:41], v[146:149], v[170:173], v[38:41]
	v_mfma_f32_16x16x32_bf16 v[34:37], v[154:157], v[170:173], v[34:37]
	v_mfma_f32_16x16x32_bf16 v[22:25], v[146:149], v[184:187], v[22:25]
	v_mfma_f32_16x16x32_bf16 v[18:21], v[154:157], v[184:187], v[18:21]
	v_mfma_f32_16x16x32_bf16 v[6:9], v[146:149], v[192:195], v[6:9]
	v_mfma_f32_16x16x32_bf16 v[2:5], v[154:157], v[192:195], v[2:5]
	v_mfma_f32_16x16x32_bf16 v[66:69], v[158:161], v[166:169], v[50:53]
	v_mfma_f32_16x16x32_bf16 v[38:41], v[150:153], v[180:183], v[38:41]
	v_mfma_f32_16x16x32_bf16 v[34:37], v[158:161], v[180:183], v[34:37]
	v_mfma_f32_16x16x32_bf16 v[22:25], v[150:153], v[188:191], v[22:25]
	v_mfma_f32_16x16x32_bf16 v[18:21], v[158:161], v[188:191], v[18:21]
	v_mfma_f32_16x16x32_bf16 v[6:9], v[150:153], v[196:199], v[6:9]
	v_mfma_f32_16x16x32_bf16 v[2:5], v[158:161], v[196:199], v[2:5]
	s_setprio 0
	s_barrier
	s_add_i32 s29, s29, 2
	s_add_u32 s27, s27, 0x100
	s_addc_u32 s28, s28, 0
	s_cmpk_gt_u32 s29, 0x53
	s_mov_b64 s[46:47], s[4:5]
	s_cbranch_scc0 .LBB0_1498
	s_and_b64 vcc, exec, s[54:55]
	s_cbranch_vccz .LBB0_1501
	s_barrier
